# rwprep stage3: next token's row loads prefetched one token ahead into spare VGPRs (no store->load serialization); stage1 loads hoisted; RWKV static scan loop hand-scheduled
# speedup vs baseline: 1.0109x; 1.0109x over previous
.LBB0_195:
	s_or_b64 exec, exec, s[16:17]
	v_add_u32_e32 v102, s20, v133
	v_mad_i64_i32 v[52:53], s[10:11], v102, s22, v[60:61]
	global_load_dwordx2 v[104:105], v[52:53], off
	global_load_dwordx2 v[120:121], v[52:53], off offset:2048
	v_add_co_u32_e32 v52, vcc, s2, v52
	s_waitcnt vmcnt(1)
	v_lshlrev_b32_e32 v118, 16, v104
	v_addc_co_u32_e32 v53, vcc, 0, v53, vcc
	global_load_dwordx2 v[108:109], v[52:53], off
	global_load_dwordx2 v[116:117], v[52:53], off offset:2048
	v_add_u32_e32 v246, 1, v102
	v_mad_i64_i32 v[242:243], s[26:27], v246, s22, v[60:61]
	global_load_dwordx2 v[234:235], v[242:243], off
	global_load_dwordx2 v[236:237], v[242:243], off offset:2048
	v_add_co_u32_e32 v244, vcc, s2, v242
	s_nop 1
	v_addc_co_u32_e32 v245, vcc, 0, v243, vcc
	global_load_dwordx2 v[238:239], v[244:245], off
	global_load_dwordx2 v[240:241], v[244:245], off offset:2048
	ds_read2st64_b64 v[52:55], v166 offset0:16 offset1:80
	v_and_b32_e32 v119, 0xffff0000, v104
	s_waitcnt vmcnt(6)
	v_lshlrev_b32_e32 v114, 16, v120
	v_and_b32_e32 v115, 0xffff0000, v120
	v_pk_add_f32 v[44:45], v[44:45], v[118:119] neg_lo:[0,1] neg_hi:[0,1]
	s_waitcnt lgkmcnt(0)
	v_lshlrev_b32_e32 v58, 16, v54
	v_and_b32_e32 v54, 0xffff0000, v54
	v_lshlrev_b32_e32 v103, 16, v55
	v_and_b32_e32 v55, 0xffff0000, v55
	v_add_f32_e32 v58, v12, v58
	v_add_f32_e32 v54, v13, v54
	v_add_f32_e32 v103, v14, v103
	v_add_f32_e32 v55, v15, v55
	v_mul_f32_e32 v58, 0xbfb8aa3b, v58
	v_mul_f32_e32 v54, 0xbfb8aa3b, v54
	v_mul_f32_e32 v103, 0xbfb8aa3b, v103
	v_mul_f32_e32 v55, 0xbfb8aa3b, v55
	v_exp_f32_e32 v58, v58
	v_exp_f32_e32 v54, v54
	v_exp_f32_e32 v103, v103
	v_exp_f32_e32 v55, v55
	v_add_f32_e32 v58, 1.0, v58
	v_add_f32_e32 v54, 1.0, v54
	v_add_f32_e32 v103, 1.0, v103
	v_add_f32_e32 v55, 1.0, v55
	v_rcp_f32_e32 v112, v58
	v_rcp_f32_e32 v113, v54
	v_rcp_f32_e32 v110, v103
	v_rcp_f32_e32 v111, v55
	v_pk_add_f32 v[48:49], v[48:49], v[114:115] neg_lo:[0,1] neg_hi:[0,1]
	v_pk_add_f32 v[54:55], v[112:113], -1.0 op_sel_hi:[1,0]
	v_pk_fma_f32 v[122:123], v[16:17], v[44:45], v[118:119]
	v_pk_add_f32 v[106:107], v[110:111], -1.0 op_sel_hi:[1,0]
	v_pk_fma_f32 v[124:125], v[28:29], v[54:55], 1.0 op_sel_hi:[1,1,0]
	v_lshlrev_b32_e32 v54, 16, v121
	v_and_b32_e32 v55, 0xffff0000, v121
	v_pk_fma_f32 v[44:45], v[20:21], v[48:49], v[114:115]
	v_pk_fma_f32 v[148:149], v[30:31], v[106:107], 1.0 op_sel_hi:[1,1,0]
	v_lshlrev_b32_e32 v106, 16, v105
	v_and_b32_e32 v107, 0xffff0000, v105
	v_pk_add_f32 v[50:51], v[50:51], v[54:55] neg_lo:[0,1] neg_hi:[0,1]
	v_pk_mul_f32 v[120:121], v[44:45], v[124:125]
	v_pk_add_f32 v[46:47], v[46:47], v[106:107] neg_lo:[0,1] neg_hi:[0,1]
	v_pk_fma_f32 v[50:51], v[22:23], v[50:51], v[54:55]
	v_pk_mul_f32 v[126:127], v[24:25], v[44:45]
	v_pk_mul_f32 v[44:45], v[122:123], v[120:121]
	v_pk_fma_f32 v[46:47], v[18:19], v[46:47], v[106:107]
	v_pk_mul_f32 v[48:49], v[50:51], v[148:149]
	v_pk_mul_f32 v[124:125], v[26:27], v[50:51]
	v_pk_mul_f32 v[50:51], v[126:127], v[126:127]
	v_fma_f32 v44, v32, v44, 0
	v_pk_mul_f32 v[104:105], v[46:47], v[48:49]
	v_pk_mul_f32 v[148:149], v[124:125], v[124:125]
	v_add_f32_e32 v50, v50, v51
	v_fmac_f32_e32 v44, v33, v45
	v_add_f32_e32 v45, v50, v148
	v_fmac_f32_e32 v44, v34, v104
	v_add_f32_e32 v45, v149, v45
	v_fmac_f32_e32 v44, v35, v105
	v_ashrrev_i32_e32 v103, 31, v102
	v_add_f32_dpp v45, v45, v45 quad_perm:[1,0,3,2] row_mask:0xf bank_mask:0xf bound_ctrl:1
	v_add_f32_dpp v44, v44, v44 quad_perm:[1,0,3,2] row_mask:0xf bank_mask:0xf bound_ctrl:1
	s_nop 0
	v_add_f32_dpp v45, v45, v45 quad_perm:[2,3,0,1] row_mask:0xf bank_mask:0xf bound_ctrl:1
	v_add_f32_dpp v44, v44, v44 quad_perm:[2,3,0,1] row_mask:0xf bank_mask:0xf bound_ctrl:1
	s_nop 0
	v_add_f32_dpp v58, v45, v45 row_half_mirror row_mask:0xf bank_mask:0xf bound_ctrl:1
	v_add_f32_dpp v44, v44, v44 row_half_mirror row_mask:0xf bank_mask:0xf bound_ctrl:1
	s_nop 0
	v_mov_b32_dpp v148, v58 row_mirror row_mask:0xf bank_mask:0xf bound_ctrl:1
	v_mov_b32_dpp v45, v44 row_mirror row_mask:0xf bank_mask:0xf bound_ctrl:1
	s_and_saveexec_b64 s[10:11], s[6:7]
	s_cbranch_execz .LBB0_197
	v_lshlrev_b64 v[50:51], 6, v[102:103]
	v_lshl_add_u64 v[50:51], v[98:99], 0, v[50:51]
	v_add_f32_e32 v44, v44, v45
	global_store_dword v[50:51], v44, off
.LBB0_197:
	s_or_b64 exec, exec, s[10:11]
	v_lshlrev_b32_e32 v50, 16, v52
	v_add_f32_e32 v50, v8, v50
	v_mul_f32_e32 v50, 0xbfb8aa3b, v50
	v_exp_f32_e32 v103, v50
	s_waitcnt vmcnt(4)
	v_lshlrev_b32_e32 v104, 16, v108
	v_and_b32_e32 v105, 0xffff0000, v108
	v_lshlrev_b32_e32 v44, 16, v109
	v_add_f32_e32 v103, 1.0, v103
	v_rcp_f32_e32 v103, v103
	v_and_b32_e32 v45, 0xffff0000, v109
	s_waitcnt vmcnt(4)
	v_lshlrev_b32_e32 v108, 16, v116
	v_and_b32_e32 v109, 0xffff0000, v116
	v_pk_add_f32 v[40:41], v[40:41], v[108:109] neg_lo:[0,1] neg_hi:[0,1]
	v_and_b32_e32 v116, 0xffff0000, v52
	v_pk_fma_f32 v[40:41], v[4:5], v[40:41], v[108:109]
	v_lshlrev_b32_e32 v50, 16, v117
	v_and_b32_e32 v51, 0xffff0000, v117
	v_lshlrev_b32_e32 v117, 16, v53
	v_and_b32_e32 v149, 0xffff0000, v53
	v_mul_f32_e32 v52, 0xbf1b4598, v103
	v_mul_f32_e32 v53, 0xbfb8aa3b, v40
	v_add_f32_e32 v103, v9, v116
	v_exp_f32_e32 v53, v53
	v_mul_f32_e32 v103, 0xbfb8aa3b, v103
	v_exp_f32_e32 v103, v103
	v_add_f32_e32 v117, v10, v117
	v_add_f32_e32 v53, 1.0, v53
	v_rcp_f32_e32 v116, v53
	v_add_f32_e32 v53, 1.0, v103
	v_mul_f32_e32 v103, 0xbfb8aa3b, v41
	v_exp_f32_e32 v103, v103
	v_mul_f32_e32 v117, 0xbfb8aa3b, v117
	v_exp_f32_e32 v150, v117
	v_rcp_f32_e32 v53, v53
	v_add_f32_e32 v103, 1.0, v103
	v_rcp_f32_e32 v117, v103
	v_add_f32_e32 v103, 1.0, v150
	v_rcp_f32_e32 v103, v103
	v_mul_f32_e32 v53, 0xbf1b4598, v53
	v_pk_mul_f32 v[40:41], v[40:41], v[116:117]
	v_add_f32_e32 v116, v11, v149
	v_mul_f32_e32 v116, 0xbfb8aa3b, v116
	v_exp_f32_e32 v116, v116
	v_mul_f32_e32 v52, 0x3fb8aa3b, v52
	v_mul_f32_e32 v53, 0x3fb8aa3b, v53
	v_exp_f32_e32 v52, v52
	v_add_f32_e32 v116, 1.0, v116
	v_rcp_f32_e32 v116, v116
	v_exp_f32_e32 v53, v53
	v_mul_f32_e32 v103, 0xbf1b4598, v103
	v_pk_add_f32 v[42:43], v[42:43], v[50:51] neg_lo:[0,1] neg_hi:[0,1]
	v_mul_f32_e32 v103, 0x3fb8aa3b, v103
	v_pk_fma_f32 v[42:43], v[6:7], v[42:43], v[50:51]
	v_add_f32_e32 v58, v58, v148
	v_exp_f32_e32 v150, v103
	v_mul_f32_e32 v103, 0xbfb8aa3b, v42
	v_mul_f32_e32 v116, 0xbf1b4598, v116
	v_max_f32_e32 v58, 0x179abe15, v58
	v_exp_f32_e32 v103, v103
	v_mul_f32_e32 v116, 0x3fb8aa3b, v116
	v_rsq_f32_e32 v58, v58
	v_pk_add_f32 v[52:53], v[52:53], -1.0 op_sel_hi:[1,0]
	v_exp_f32_e32 v151, v116
	v_pk_add_f32 v[116:117], v[52:53], 1.0 op_sel_hi:[1,0]
	v_add_f32_e32 v103, 1.0, v103
	v_rcp_f32_e32 v52, v116
	v_rcp_f32_e32 v53, v117
	v_pk_mul_f32 v[126:127], v[126:127], v[58:59] op_sel_hi:[1,0]
	v_rcp_f32_e32 v152, v103
	v_mul_f32_e32 v103, 0xbfb8aa3b, v43
	v_pk_mul_f32 v[112:113], v[112:113], v[126:127]
	v_exp_f32_e32 v103, v103
	v_pk_mul_f32 v[148:149], v[52:53], v[112:113]
	v_pk_add_f32 v[112:113], v[150:151], -1.0 op_sel_hi:[1,0]
	v_pk_add_f32 v[36:37], v[36:37], v[104:105] neg_lo:[0,1] neg_hi:[0,1]
	v_pk_add_f32 v[112:113], v[112:113], 1.0 op_sel_hi:[1,0]
	v_add_f32_e32 v103, 1.0, v103
	v_rcp_f32_e32 v150, v112
	v_rcp_f32_e32 v151, v113
	v_pk_add_f32 v[38:39], v[38:39], v[44:45] neg_lo:[0,1] neg_hi:[0,1]
	v_rcp_f32_e32 v153, v103
	v_pk_mul_f32 v[122:123], v[122:123], v[116:117]
	v_pk_mul_f32 v[52:53], v[52:53], v[120:121]
	v_pk_mul_f32 v[120:121], v[124:125], v[58:59] op_sel_hi:[1,0]
	v_pk_mul_f32 v[46:47], v[46:47], v[112:113]
	v_mad_i64_i32 v[124:125], s[10:11], v102, s23, v[56:57]
	v_pk_fma_f32 v[36:37], v[0:1], v[36:37], v[104:105]
	v_pk_fma_f32 v[38:39], v[2:3], v[38:39], v[44:45]
	v_pk_mul_f32 v[48:49], v[150:151], v[48:49]
	v_cvt_pk_bf16_f32 v122, v122, v123
	v_cvt_pk_bf16_f32 v123, v46, v47
	v_lshlrev_b64 v[46:47], 1, v[124:125]
	v_pk_mul_f32 v[110:111], v[110:111], v[120:121]
	v_lshl_add_u64 v[124:125], s[74:75], 0, v[46:47]
	v_cvt_pk_bf16_f32 v52, v52, v53
	v_cvt_pk_bf16_f32 v53, v48, v49
	v_lshl_add_u64 v[48:49], s[76:77], 0, v[46:47]
	v_cvt_pk_bf16_f32 v36, v36, v37
	v_cvt_pk_bf16_f32 v37, v38, v39
	v_lshl_add_u64 v[38:39], s[78:79], 0, v[46:47]
	v_pk_mul_f32 v[110:111], v[110:111], v[150:151]
	global_store_dwordx2 v[124:125], v[122:123], off
	global_store_dwordx2 v[48:49], v[52:53], off
	global_store_dwordx2 v[38:39], v[36:37], off
	v_cvt_pk_bf16_f32 v36, v126, v127
	v_cvt_pk_bf16_f32 v37, v120, v121
	v_lshl_add_u64 v[38:39], s[80:81], 0, v[46:47]
	v_pk_mul_f32 v[42:43], v[42:43], v[152:153]
	global_store_dwordx2 v[38:39], v[36:37], off
	v_cvt_pk_bf16_f32 v36, v148, v149
	v_cvt_pk_bf16_f32 v37, v110, v111
	v_lshl_add_u64 v[38:39], s[82:83], 0, v[46:47]
	global_store_dwordx2 v[38:39], v[36:37], off
	v_cvt_pk_bf16_f32 v36, v40, v41
	v_cvt_pk_bf16_f32 v37, v42, v43
	v_lshl_add_u64 v[38:39], s[84:85], 0, v[46:47]
	v_add_u32_e32 v120, 1, v102
	global_store_dwordx2 v[38:39], v[36:37], off
	v_mad_i64_i32 v[36:37], s[10:11], v120, s22, v[60:61]
	v_add_co_u32_e32 v36, vcc, s2, v36
	v_ashrrev_i32_e32 v121, 31, v120
	s_nop 0
	v_addc_co_u32_e32 v37, vcc, 0, v37, vcc
	s_waitcnt vmcnt(6)
	v_mov_b64_e32 v[40:41], v[234:235]
	v_mov_b64_e32 v[46:47], v[236:237]
	v_mov_b64_e32 v[42:43], v[238:239]
	v_mov_b64_e32 v[48:49], v[240:241]
	v_add_u32_e32 v246, 2, v102
	v_mad_i64_i32 v[242:243], s[26:27], v246, s22, v[60:61]
	global_load_dwordx2 v[234:235], v[242:243], off
	global_load_dwordx2 v[236:237], v[242:243], off offset:2048
	v_add_co_u32_e32 v244, vcc, s2, v242
	s_nop 1
	v_addc_co_u32_e32 v245, vcc, 0, v243, vcc
	global_load_dwordx2 v[238:239], v[244:245], off
	global_load_dwordx2 v[240:241], v[244:245], off offset:2048
	ds_read2st64_b64 v[36:39], v167 offset0:16 offset1:80
	s_waitcnt lgkmcnt(0)
	v_lshlrev_b32_e32 v58, 16, v38
	v_and_b32_e32 v38, 0xffff0000, v38
	v_add_f32_e32 v38, v13, v38
	v_mul_f32_e32 v38, 0xbfb8aa3b, v38
	v_lshlrev_b32_e32 v103, 16, v39
	v_and_b32_e32 v126, 0xffff0000, v39
	v_add_f32_e32 v39, v12, v58
	v_exp_f32_e32 v58, v38
	v_mul_f32_e32 v39, 0xbfb8aa3b, v39
	v_exp_f32_e32 v39, v39
	v_add_f32_e32 v58, 1.0, v58
	v_rcp_f32_e32 v123, v58
	v_add_f32_e32 v58, v14, v103
	v_mul_f32_e32 v58, 0xbfb8aa3b, v58
	v_add_f32_e32 v103, v15, v126
	v_add_f32_e32 v38, 1.0, v39
	v_exp_f32_e32 v58, v58
	v_mul_f32_e32 v103, 0xbfb8aa3b, v103
	v_rcp_f32_e32 v122, v38
	v_exp_f32_e32 v103, v103
	v_add_f32_e32 v58, 1.0, v58
	v_rcp_f32_e32 v126, v58
	v_add_f32_e32 v58, 1.0, v103
	v_rcp_f32_e32 v127, v58
	v_lshlrev_b32_e32 v52, 16, v40
	v_and_b32_e32 v53, 0xffff0000, v40
	v_lshlrev_b32_e32 v110, 16, v46
	v_and_b32_e32 v111, 0xffff0000, v46
	v_pk_add_f32 v[38:39], v[118:119], v[52:53] neg_lo:[0,1] neg_hi:[0,1]
	v_pk_add_f32 v[114:115], v[114:115], v[110:111] neg_lo:[0,1] neg_hi:[0,1]
	v_pk_add_f32 v[118:119], v[122:123], -1.0 op_sel_hi:[1,0]
	v_pk_fma_f32 v[114:115], v[20:21], v[114:115], v[110:111]
	v_pk_fma_f32 v[118:119], v[28:29], v[118:119], 1.0 op_sel_hi:[1,1,0]
	v_pk_fma_f32 v[38:39], v[16:17], v[38:39], v[52:53]
	v_pk_mul_f32 v[118:119], v[114:115], v[118:119]
	v_lshlrev_b32_e32 v40, 16, v41
	v_and_b32_e32 v41, 0xffff0000, v41
	v_lshlrev_b32_e32 v46, 16, v47
	v_and_b32_e32 v47, 0xffff0000, v47
	v_pk_mul_f32 v[124:125], v[38:39], v[118:119]
	v_pk_add_f32 v[106:107], v[106:107], v[40:41] neg_lo:[0,1] neg_hi:[0,1]
	v_fma_f32 v154, v32, v124, 0
	v_pk_add_f32 v[54:55], v[54:55], v[46:47] neg_lo:[0,1] neg_hi:[0,1]
	v_pk_mul_f32 v[148:149], v[24:25], v[114:115]
	v_fmac_f32_e32 v154, v33, v125
	v_pk_fma_f32 v[124:125], v[18:19], v[106:107], v[40:41]
	v_pk_fma_f32 v[54:55], v[22:23], v[54:55], v[46:47]
	v_pk_add_f32 v[106:107], v[126:127], -1.0 op_sel_hi:[1,0]
	v_pk_mul_f32 v[114:115], v[148:149], v[148:149]
	v_pk_fma_f32 v[106:107], v[30:31], v[106:107], 1.0 op_sel_hi:[1,1,0]
	v_pk_mul_f32 v[152:153], v[26:27], v[54:55]
	v_pk_mul_f32 v[150:151], v[54:55], v[106:107]
	v_pk_mul_f32 v[54:55], v[152:153], v[152:153]
	v_add_f32_e32 v58, v114, v115
	v_add_f32_e32 v54, v58, v54
	v_pk_mul_f32 v[106:107], v[124:125], v[150:151]
	v_add_f32_e32 v54, v55, v54
	v_fmac_f32_e32 v154, v34, v106
	v_fmac_f32_e32 v154, v35, v107
	v_add_f32_dpp v54, v54, v54 quad_perm:[1,0,3,2] row_mask:0xf bank_mask:0xf bound_ctrl:1
	s_nop 1
	v_add_f32_dpp v54, v54, v54 quad_perm:[2,3,0,1] row_mask:0xf bank_mask:0xf bound_ctrl:1
	s_nop 1
	v_add_f32_dpp v58, v54, v54 row_half_mirror row_mask:0xf bank_mask:0xf bound_ctrl:1
	v_add_f32_dpp v54, v154, v154 quad_perm:[1,0,3,2] row_mask:0xf bank_mask:0xf bound_ctrl:1
	s_nop 0
	v_mov_b32_dpp v103, v58 row_mirror row_mask:0xf bank_mask:0xf bound_ctrl:1
	v_add_f32_dpp v54, v54, v54 quad_perm:[2,3,0,1] row_mask:0xf bank_mask:0xf bound_ctrl:1
	s_nop 1
	v_add_f32_dpp v54, v54, v54 row_half_mirror row_mask:0xf bank_mask:0xf bound_ctrl:1
	s_nop 1
	v_mov_b32_dpp v55, v54 row_mirror row_mask:0xf bank_mask:0xf bound_ctrl:1
	s_and_saveexec_b64 s[10:11], s[6:7]
	s_cbranch_execz .LBB0_199
	v_lshlrev_b64 v[106:107], 6, v[120:121]
	v_lshl_add_u64 v[106:107], v[98:99], 0, v[106:107]
	v_add_f32_e32 v54, v54, v55
	global_store_dword v[106:107], v54, off
.LBB0_199:
	s_or_b64 exec, exec, s[10:11]
	v_lshlrev_b32_e32 v107, 16, v36
	v_add_f32_e32 v107, v8, v107
	v_mul_f32_e32 v107, 0xbfb8aa3b, v107
	v_exp_f32_e32 v114, v107
	v_lshlrev_b32_e32 v106, 16, v48
	v_and_b32_e32 v107, 0xffff0000, v48
	v_pk_add_f32 v[108:109], v[108:109], v[106:107] neg_lo:[0,1] neg_hi:[0,1]
	v_add_f32_e32 v114, 1.0, v114
	v_rcp_f32_e32 v114, v114
	v_and_b32_e32 v115, 0xffff0000, v36
	v_pk_fma_f32 v[108:109], v[4:5], v[108:109], v[106:107]
	v_lshlrev_b32_e32 v121, 16, v37
	v_and_b32_e32 v155, 0xffff0000, v37
	v_mul_f32_e32 v36, 0xbf1b4598, v114
	v_mul_f32_e32 v37, 0xbfb8aa3b, v108
	v_add_f32_e32 v114, v9, v115
	v_exp_f32_e32 v37, v37
	v_mul_f32_e32 v114, 0xbfb8aa3b, v114
	v_exp_f32_e32 v115, v114
	v_add_f32_e32 v121, v10, v121
	v_add_f32_e32 v37, 1.0, v37
	v_rcp_f32_e32 v114, v37
	v_add_f32_e32 v37, 1.0, v115
	v_mul_f32_e32 v115, 0xbfb8aa3b, v109
	v_mul_f32_e32 v121, 0xbfb8aa3b, v121
	v_exp_f32_e32 v115, v115
	v_exp_f32_e32 v121, v121
	v_lshlrev_b32_e32 v48, 16, v49
	v_and_b32_e32 v49, 0xffff0000, v49
	v_add_f32_e32 v115, 1.0, v115
	v_add_f32_e32 v121, 1.0, v121
	v_rcp_f32_e32 v115, v115
	v_rcp_f32_e32 v121, v121
	v_rcp_f32_e32 v37, v37
	v_pk_add_f32 v[50:51], v[50:51], v[48:49] neg_lo:[0,1] neg_hi:[0,1]
	v_pk_mul_f32 v[108:109], v[108:109], v[114:115]
	v_mul_f32_e32 v114, 0xbf1b4598, v121
	v_add_f32_e32 v115, v11, v155
	v_mul_f32_e32 v114, 0x3fb8aa3b, v114
	v_pk_fma_f32 v[50:51], v[6:7], v[50:51], v[48:49]
	v_mul_f32_e32 v115, 0xbfb8aa3b, v115
	v_exp_f32_e32 v154, v114
	v_mul_f32_e32 v114, 0xbfb8aa3b, v50
	v_exp_f32_e32 v115, v115
	v_mul_f32_e32 v121, 0xbfb8aa3b, v51
	v_exp_f32_e32 v114, v114
	v_exp_f32_e32 v121, v121
	v_mul_f32_e32 v37, 0xbf1b4598, v37
	v_mul_f32_e32 v36, 0x3fb8aa3b, v36
	v_mul_f32_e32 v37, 0x3fb8aa3b, v37
	v_exp_f32_e32 v36, v36
	v_exp_f32_e32 v37, v37
	v_add_f32_e32 v115, 1.0, v115
	v_add_f32_e32 v114, 1.0, v114
	v_rcp_f32_e32 v155, v115
	v_add_f32_e32 v115, 1.0, v121
	v_rcp_f32_e32 v114, v114
	v_rcp_f32_e32 v115, v115
	v_add_f32_e32 v58, v58, v103
	v_max_f32_e32 v58, 0x179abe15, v58
	v_pk_add_f32 v[36:37], v[36:37], -1.0 op_sel_hi:[1,0]
	v_mul_f32_e32 v121, 0xbf1b4598, v155
	v_rsq_f32_e32 v58, v58
	v_pk_add_f32 v[36:37], v[36:37], 1.0 op_sel_hi:[1,0]
	v_mul_f32_e32 v121, 0x3fb8aa3b, v121
	v_pk_mul_f32 v[50:51], v[50:51], v[114:115]
	v_pk_mul_f32 v[114:115], v[116:117], v[36:37]
	v_exp_f32_e32 v155, v121
	v_rcp_f32_e32 v36, v114
	v_rcp_f32_e32 v37, v115
	v_pk_mul_f32 v[148:149], v[148:149], v[58:59] op_sel_hi:[1,0]
	v_mad_i64_i32 v[120:121], s[10:11], v120, s23, v[56:57]
	v_pk_mul_f32 v[178:179], v[116:117], v[148:149]
	v_pk_mul_f32 v[116:117], v[122:123], v[148:149]
	v_pk_mul_f32 v[148:149], v[152:153], v[58:59] op_sel_hi:[1,0]
	v_pk_mul_f32 v[122:123], v[116:117], v[36:37]
	v_pk_add_f32 v[116:117], v[154:155], -1.0 op_sel_hi:[1,0]
	v_pk_mul_f32 v[36:37], v[118:119], v[36:37]
	v_pk_add_f32 v[116:117], v[116:117], 1.0 op_sel_hi:[1,0]
	v_lshlrev_b32_e32 v54, 16, v42
	v_pk_mul_f32 v[116:117], v[112:113], v[116:117]
	v_and_b32_e32 v55, 0xffff0000, v42
	v_rcp_f32_e32 v118, v116
	v_rcp_f32_e32 v119, v117
	v_lshlrev_b32_e32 v42, 16, v43
	v_and_b32_e32 v43, 0xffff0000, v43
	v_pk_mul_f32 v[38:39], v[38:39], v[114:115]
	v_pk_mul_f32 v[126:127], v[126:127], v[148:149]
	v_pk_mul_f32 v[124:125], v[124:125], v[116:117]
	v_lshlrev_b64 v[120:121], 1, v[120:121]
	v_pk_add_f32 v[104:105], v[104:105], v[54:55] neg_lo:[0,1] neg_hi:[0,1]
	v_pk_add_f32 v[44:45], v[44:45], v[42:43] neg_lo:[0,1] neg_hi:[0,1]
	v_pk_mul_f32 v[126:127], v[126:127], v[118:119]
	v_pk_mul_f32 v[118:119], v[150:151], v[118:119]
	v_cvt_pk_bf16_f32 v38, v38, v39
	v_cvt_pk_bf16_f32 v39, v124, v125
	v_lshl_add_u64 v[124:125], s[74:75], 0, v[120:121]
	v_pk_fma_f32 v[104:105], v[0:1], v[104:105], v[54:55]
	v_pk_fma_f32 v[44:45], v[2:3], v[44:45], v[42:43]
	global_store_dwordx2 v[124:125], v[38:39], off
	v_cvt_pk_bf16_f32 v36, v36, v37
	v_cvt_pk_bf16_f32 v37, v118, v119
	v_lshl_add_u64 v[38:39], s[76:77], 0, v[120:121]
	v_pk_mul_f32 v[112:113], v[112:113], v[148:149]
	global_store_dwordx2 v[38:39], v[36:37], off
	v_cvt_pk_bf16_f32 v36, v104, v105
	v_cvt_pk_bf16_f32 v37, v44, v45
	v_lshl_add_u64 v[38:39], s[78:79], 0, v[120:121]
	global_store_dwordx2 v[38:39], v[36:37], off
	v_cvt_pk_bf16_f32 v36, v178, v179
	v_cvt_pk_bf16_f32 v37, v112, v113
	v_lshl_add_u64 v[38:39], s[80:81], 0, v[120:121]
	global_store_dwordx2 v[38:39], v[36:37], off
	v_cvt_pk_bf16_f32 v36, v122, v123
	v_cvt_pk_bf16_f32 v37, v126, v127
	v_lshl_add_u64 v[38:39], s[82:83], 0, v[120:121]
	global_store_dwordx2 v[38:39], v[36:37], off
	v_cvt_pk_bf16_f32 v36, v108, v109
	v_cvt_pk_bf16_f32 v37, v50, v51
	v_lshl_add_u64 v[38:39], s[84:85], 0, v[120:121]
	v_add_u32_e32 v122, 2, v102
	global_store_dwordx2 v[38:39], v[36:37], off
	v_mad_i64_i32 v[36:37], s[10:11], v122, s22, v[60:61]
	v_add_co_u32_e32 v36, vcc, s2, v36
	v_ashrrev_i32_e32 v123, 31, v122
	s_nop 0
	v_addc_co_u32_e32 v37, vcc, 0, v37, vcc
	s_waitcnt vmcnt(6)
	v_mov_b64_e32 v[44:45], v[234:235]
	v_mov_b64_e32 v[50:51], v[236:237]
	v_mov_b64_e32 v[154:155], v[238:239]
	v_mov_b64_e32 v[118:119], v[240:241]
	v_add_u32_e32 v246, 3, v102
	v_mad_i64_i32 v[242:243], s[26:27], v246, s22, v[60:61]
	global_load_dwordx2 v[234:235], v[242:243], off
	global_load_dwordx2 v[236:237], v[242:243], off offset:2048
	v_add_co_u32_e32 v244, vcc, s2, v242
	s_nop 1
	v_addc_co_u32_e32 v245, vcc, 0, v243, vcc
	global_load_dwordx2 v[238:239], v[244:245], off
	global_load_dwordx2 v[240:241], v[244:245], off offset:2048
	ds_read2st64_b64 v[36:39], v168 offset0:16 offset1:80
	s_waitcnt lgkmcnt(0)
	v_lshlrev_b32_e32 v58, 16, v38
	v_and_b32_e32 v38, 0xffff0000, v38
	v_lshlrev_b32_e32 v103, 16, v39
	v_and_b32_e32 v126, 0xffff0000, v39
	v_add_f32_e32 v39, v12, v58
	v_mul_f32_e32 v39, 0xbfb8aa3b, v39
	v_add_f32_e32 v38, v13, v38
	v_exp_f32_e32 v39, v39
	v_mul_f32_e32 v38, 0xbfb8aa3b, v38
	v_exp_f32_e32 v58, v38
	v_add_f32_e32 v38, 1.0, v39
	v_rcp_f32_e32 v120, v38
	v_lshlrev_b32_e32 v108, 16, v44
	v_and_b32_e32 v109, 0xffff0000, v44
	v_pk_add_f32 v[38:39], v[52:53], v[108:109] neg_lo:[0,1] neg_hi:[0,1]
	v_add_f32_e32 v52, 1.0, v58
	v_add_f32_e32 v58, v14, v103
	v_mul_f32_e32 v58, 0xbfb8aa3b, v58
	v_add_f32_e32 v103, v15, v126
	v_exp_f32_e32 v58, v58
	v_mul_f32_e32 v103, 0xbfb8aa3b, v103
	v_exp_f32_e32 v103, v103
	v_rcp_f32_e32 v121, v52
	v_add_f32_e32 v58, 1.0, v58
	v_rcp_f32_e32 v148, v58
	v_add_f32_e32 v58, 1.0, v103
	v_rcp_f32_e32 v149, v58
	v_lshlrev_b32_e32 v44, 16, v45
	v_and_b32_e32 v45, 0xffff0000, v45
	v_lshlrev_b32_e32 v112, 16, v50
	v_and_b32_e32 v113, 0xffff0000, v50
	v_lshlrev_b32_e32 v50, 16, v51
	v_and_b32_e32 v51, 0xffff0000, v51
	v_pk_add_f32 v[52:53], v[110:111], v[112:113] neg_lo:[0,1] neg_hi:[0,1]
	v_pk_add_f32 v[40:41], v[40:41], v[44:45] neg_lo:[0,1] neg_hi:[0,1]
	v_pk_fma_f32 v[52:53], v[20:21], v[52:53], v[112:113]
	v_pk_add_f32 v[104:105], v[120:121], -1.0 op_sel_hi:[1,0]
	v_pk_fma_f32 v[126:127], v[18:19], v[40:41], v[44:45]
	v_pk_add_f32 v[40:41], v[46:47], v[50:51] neg_lo:[0,1] neg_hi:[0,1]
	v_pk_fma_f32 v[104:105], v[28:29], v[104:105], 1.0 op_sel_hi:[1,1,0]
	v_pk_mul_f32 v[150:151], v[24:25], v[52:53]
	v_pk_fma_f32 v[40:41], v[22:23], v[40:41], v[50:51]
	v_pk_add_f32 v[46:47], v[148:149], -1.0 op_sel_hi:[1,0]
	v_pk_fma_f32 v[38:39], v[16:17], v[38:39], v[108:109]
	v_pk_mul_f32 v[124:125], v[52:53], v[104:105]
	v_pk_mul_f32 v[52:53], v[150:151], v[150:151]
	v_pk_fma_f32 v[46:47], v[30:31], v[46:47], 1.0 op_sel_hi:[1,1,0]
	v_pk_mul_f32 v[152:153], v[26:27], v[40:41]
	v_pk_mul_f32 v[104:105], v[38:39], v[124:125]
	v_pk_mul_f32 v[46:47], v[40:41], v[46:47]
	v_pk_mul_f32 v[40:41], v[152:153], v[152:153]
	v_add_f32_e32 v52, v52, v53
	v_fma_f32 v110, v32, v104, 0
	v_add_f32_e32 v40, v52, v40
	v_fmac_f32_e32 v110, v33, v105
	v_pk_mul_f32 v[104:105], v[126:127], v[46:47]
	v_add_f32_e32 v40, v41, v40
	v_fmac_f32_e32 v110, v34, v104
	v_fmac_f32_e32 v110, v35, v105
	v_add_f32_dpp v40, v40, v40 quad_perm:[1,0,3,2] row_mask:0xf bank_mask:0xf bound_ctrl:1
	s_nop 1
	v_add_f32_dpp v40, v40, v40 quad_perm:[2,3,0,1] row_mask:0xf bank_mask:0xf bound_ctrl:1
	s_nop 1
	v_add_f32_dpp v58, v40, v40 row_half_mirror row_mask:0xf bank_mask:0xf bound_ctrl:1
	v_add_f32_dpp v40, v110, v110 quad_perm:[1,0,3,2] row_mask:0xf bank_mask:0xf bound_ctrl:1
	s_nop 0
	v_mov_b32_dpp v103, v58 row_mirror row_mask:0xf bank_mask:0xf bound_ctrl:1
	v_add_f32_dpp v40, v40, v40 quad_perm:[2,3,0,1] row_mask:0xf bank_mask:0xf bound_ctrl:1
	s_nop 1
	v_add_f32_dpp v40, v40, v40 row_half_mirror row_mask:0xf bank_mask:0xf bound_ctrl:1
	s_nop 1
	v_mov_b32_dpp v41, v40 row_mirror row_mask:0xf bank_mask:0xf bound_ctrl:1
	s_and_saveexec_b64 s[10:11], s[6:7]
	s_cbranch_execz .LBB0_201
	v_lshlrev_b64 v[52:53], 6, v[122:123]
	v_lshl_add_u64 v[52:53], v[98:99], 0, v[52:53]
	v_add_f32_e32 v40, v40, v41
	global_store_dword v[52:53], v40, off
.LBB0_201:
	s_or_b64 exec, exec, s[10:11]
	v_lshlrev_b32_e32 v52, 16, v36
	v_add_f32_e32 v52, v8, v52
	v_mul_f32_e32 v52, 0xbfb8aa3b, v52
	v_exp_f32_e32 v123, v52
	v_lshlrev_b32_e32 v110, 16, v118
	v_and_b32_e32 v111, 0xffff0000, v118
	v_pk_add_f32 v[106:107], v[106:107], v[110:111] neg_lo:[0,1] neg_hi:[0,1]
	v_add_f32_e32 v118, 1.0, v123
	v_rcp_f32_e32 v118, v118
	v_lshlrev_b32_e32 v52, 16, v119
	v_and_b32_e32 v53, 0xffff0000, v119
	v_and_b32_e32 v119, 0xffff0000, v36
	v_pk_fma_f32 v[106:107], v[4:5], v[106:107], v[110:111]
	v_lshlrev_b32_e32 v40, 16, v155
	v_and_b32_e32 v41, 0xffff0000, v155
	v_lshlrev_b32_e32 v123, 16, v37
	v_and_b32_e32 v155, 0xffff0000, v37
	v_mul_f32_e32 v36, 0xbf1b4598, v118
	v_mul_f32_e32 v37, 0xbfb8aa3b, v106
	v_add_f32_e32 v118, v9, v119
	v_exp_f32_e32 v37, v37
	v_mul_f32_e32 v118, 0xbfb8aa3b, v118
	v_exp_f32_e32 v119, v118
	v_add_f32_e32 v123, v10, v123
	v_add_f32_e32 v37, 1.0, v37
	v_rcp_f32_e32 v118, v37
	v_add_f32_e32 v37, 1.0, v119
	v_mul_f32_e32 v119, 0xbfb8aa3b, v107
	v_mul_f32_e32 v123, 0xbfb8aa3b, v123
	v_exp_f32_e32 v119, v119
	v_exp_f32_e32 v123, v123
	v_rcp_f32_e32 v37, v37
	v_pk_add_f32 v[48:49], v[48:49], v[52:53] neg_lo:[0,1] neg_hi:[0,1]
	v_add_f32_e32 v119, 1.0, v119
	v_add_f32_e32 v123, 1.0, v123
	v_rcp_f32_e32 v119, v119
	v_rcp_f32_e32 v123, v123
	v_pk_fma_f32 v[48:49], v[6:7], v[48:49], v[52:53]
	v_lshlrev_b32_e32 v104, 16, v154
	v_pk_mul_f32 v[106:107], v[106:107], v[118:119]
	v_mul_f32_e32 v118, 0xbf1b4598, v123
	v_add_f32_e32 v119, v11, v155
	v_mul_f32_e32 v118, 0x3fb8aa3b, v118
	v_mul_f32_e32 v119, 0xbfb8aa3b, v119
	v_and_b32_e32 v105, 0xffff0000, v154
	v_exp_f32_e32 v154, v118
	v_mul_f32_e32 v118, 0xbfb8aa3b, v48
	v_exp_f32_e32 v119, v119
	v_mul_f32_e32 v123, 0xbfb8aa3b, v49
	v_exp_f32_e32 v118, v118
	v_exp_f32_e32 v123, v123
	v_mul_f32_e32 v37, 0xbf1b4598, v37
	v_mul_f32_e32 v36, 0x3fb8aa3b, v36
	v_mul_f32_e32 v37, 0x3fb8aa3b, v37
	v_exp_f32_e32 v36, v36
	v_exp_f32_e32 v37, v37
	v_add_f32_e32 v119, 1.0, v119
	v_add_f32_e32 v118, 1.0, v118
	v_rcp_f32_e32 v155, v119
	v_add_f32_e32 v119, 1.0, v123
	v_rcp_f32_e32 v118, v118
	v_rcp_f32_e32 v119, v119
	v_add_f32_e32 v58, v58, v103
	v_max_f32_e32 v58, 0x179abe15, v58
	v_pk_add_f32 v[36:37], v[36:37], -1.0 op_sel_hi:[1,0]
	v_mul_f32_e32 v123, 0xbf1b4598, v155
	v_rsq_f32_e32 v58, v58
	v_pk_add_f32 v[36:37], v[36:37], 1.0 op_sel_hi:[1,0]
	v_mul_f32_e32 v123, 0x3fb8aa3b, v123
	v_pk_mul_f32 v[48:49], v[48:49], v[118:119]
	v_pk_mul_f32 v[118:119], v[114:115], v[36:37]
	v_exp_f32_e32 v155, v123
	v_rcp_f32_e32 v36, v118
	v_rcp_f32_e32 v37, v119
	v_pk_mul_f32 v[150:151], v[150:151], v[58:59] op_sel_hi:[1,0]
	v_pk_mul_f32 v[152:153], v[152:153], v[58:59] op_sel_hi:[1,0]
	v_pk_mul_f32 v[120:121], v[120:121], v[150:151]
	v_pk_mul_f32 v[114:115], v[114:115], v[150:151]
	v_pk_mul_f32 v[150:151], v[120:121], v[36:37]
	v_pk_add_f32 v[120:121], v[154:155], -1.0 op_sel_hi:[1,0]
	v_pk_mul_f32 v[36:37], v[124:125], v[36:37]
	v_pk_add_f32 v[120:121], v[120:121], 1.0 op_sel_hi:[1,0]
	v_mad_i64_i32 v[122:123], s[10:11], v122, s23, v[56:57]
	v_pk_mul_f32 v[120:121], v[116:117], v[120:121]
	v_pk_mul_f32 v[38:39], v[38:39], v[118:119]
	v_rcp_f32_e32 v124, v120
	v_rcp_f32_e32 v125, v121
	v_pk_mul_f32 v[148:149], v[148:149], v[152:153]
	v_pk_mul_f32 v[126:127], v[126:127], v[120:121]
	v_lshlrev_b64 v[122:123], 1, v[122:123]
	v_pk_add_f32 v[54:55], v[54:55], v[104:105] neg_lo:[0,1] neg_hi:[0,1]
	v_pk_add_f32 v[42:43], v[42:43], v[40:41] neg_lo:[0,1] neg_hi:[0,1]
	v_pk_mul_f32 v[148:149], v[148:149], v[124:125]
	v_pk_mul_f32 v[46:47], v[46:47], v[124:125]
	v_cvt_pk_bf16_f32 v38, v38, v39
	v_cvt_pk_bf16_f32 v39, v126, v127
	v_lshl_add_u64 v[124:125], s[74:75], 0, v[122:123]
	v_pk_fma_f32 v[54:55], v[0:1], v[54:55], v[104:105]
	v_pk_fma_f32 v[42:43], v[2:3], v[42:43], v[40:41]
	global_store_dwordx2 v[124:125], v[38:39], off
	v_cvt_pk_bf16_f32 v36, v36, v37
	v_cvt_pk_bf16_f32 v37, v46, v47
	v_lshl_add_u64 v[38:39], s[76:77], 0, v[122:123]
	v_pk_mul_f32 v[116:117], v[116:117], v[152:153]
	global_store_dwordx2 v[38:39], v[36:37], off
	v_cvt_pk_bf16_f32 v36, v54, v55
	v_cvt_pk_bf16_f32 v37, v42, v43
	v_lshl_add_u64 v[38:39], s[78:79], 0, v[122:123]
	global_store_dwordx2 v[38:39], v[36:37], off
	v_cvt_pk_bf16_f32 v36, v114, v115
	v_cvt_pk_bf16_f32 v37, v116, v117
	v_lshl_add_u64 v[38:39], s[80:81], 0, v[122:123]
	global_store_dwordx2 v[38:39], v[36:37], off
	v_cvt_pk_bf16_f32 v36, v150, v151
	v_cvt_pk_bf16_f32 v37, v148, v149
	v_lshl_add_u64 v[38:39], s[82:83], 0, v[122:123]
	global_store_dwordx2 v[38:39], v[36:37], off
	v_cvt_pk_bf16_f32 v36, v106, v107
	v_cvt_pk_bf16_f32 v37, v48, v49
	v_lshl_add_u64 v[38:39], s[84:85], 0, v[122:123]
	v_add_u32_e32 v122, 3, v102
	global_store_dwordx2 v[38:39], v[36:37], off
	v_mad_i64_i32 v[36:37], s[10:11], v122, s22, v[60:61]
	v_add_co_u32_e32 v36, vcc, s2, v36
	v_ashrrev_i32_e32 v123, 31, v122
	s_nop 0
	v_addc_co_u32_e32 v37, vcc, 0, v37, vcc
	s_waitcnt vmcnt(6)
	v_mov_b64_e32 v[46:47], v[234:235]
	v_mov_b64_e32 v[48:49], v[236:237]
	v_mov_b64_e32 v[42:43], v[238:239]
	v_mov_b64_e32 v[116:117], v[240:241]
	v_add_u32_e32 v246, 4, v102
	v_mad_i64_i32 v[242:243], s[26:27], v246, s22, v[60:61]
	global_load_dwordx2 v[234:235], v[242:243], off
	global_load_dwordx2 v[236:237], v[242:243], off offset:2048
	v_add_co_u32_e32 v244, vcc, s2, v242
	s_nop 1
	v_addc_co_u32_e32 v245, vcc, 0, v243, vcc
	global_load_dwordx2 v[238:239], v[244:245], off
	global_load_dwordx2 v[240:241], v[244:245], off offset:2048
	ds_read2st64_b64 v[36:39], v169 offset0:16 offset1:80
	s_waitcnt lgkmcnt(0)
	v_lshlrev_b32_e32 v54, 16, v38
	v_and_b32_e32 v38, 0xffff0000, v38
	v_lshlrev_b32_e32 v58, 16, v39
	v_and_b32_e32 v103, 0xffff0000, v39
	v_add_f32_e32 v39, v12, v54
	v_add_f32_e32 v38, v13, v38
	v_mul_f32_e32 v39, 0xbfb8aa3b, v39
	v_mul_f32_e32 v38, 0xbfb8aa3b, v38
	v_exp_f32_e32 v39, v39
	v_exp_f32_e32 v54, v38
	v_add_f32_e32 v58, v14, v58
	v_mul_f32_e32 v58, 0xbfb8aa3b, v58
	v_add_f32_e32 v103, v15, v103
	v_add_f32_e32 v38, 1.0, v39
	v_add_f32_e32 v54, 1.0, v54
	v_exp_f32_e32 v58, v58
	v_mul_f32_e32 v103, 0xbfb8aa3b, v103
	v_rcp_f32_e32 v124, v38
	v_rcp_f32_e32 v125, v54
	v_exp_f32_e32 v103, v103
	v_add_f32_e32 v58, 1.0, v58
	v_rcp_f32_e32 v126, v58
	v_add_f32_e32 v58, 1.0, v103
	v_rcp_f32_e32 v127, v58
	v_lshlrev_b32_e32 v106, 16, v46
	v_and_b32_e32 v107, 0xffff0000, v46
	v_lshlrev_b32_e32 v114, 16, v48
	v_and_b32_e32 v115, 0xffff0000, v48
	v_pk_add_f32 v[38:39], v[108:109], v[106:107] neg_lo:[0,1] neg_hi:[0,1]
	v_pk_add_f32 v[54:55], v[112:113], v[114:115] neg_lo:[0,1] neg_hi:[0,1]
	v_pk_add_f32 v[108:109], v[124:125], -1.0 op_sel_hi:[1,0]
	v_pk_fma_f32 v[54:55], v[20:21], v[54:55], v[114:115]
	v_pk_fma_f32 v[108:109], v[28:29], v[108:109], 1.0 op_sel_hi:[1,1,0]
	v_pk_fma_f32 v[38:39], v[16:17], v[38:39], v[106:107]
	v_pk_mul_f32 v[108:109], v[54:55], v[108:109]
	v_lshlrev_b32_e32 v48, 16, v49
	v_and_b32_e32 v49, 0xffff0000, v49
	v_pk_mul_f32 v[112:113], v[38:39], v[108:109]
	v_pk_add_f32 v[50:51], v[50:51], v[48:49] neg_lo:[0,1] neg_hi:[0,1]
	v_fma_f32 v154, v32, v112, 0
	v_pk_mul_f32 v[148:149], v[24:25], v[54:55]
	v_fmac_f32_e32 v154, v33, v113
	v_pk_fma_f32 v[50:51], v[22:23], v[50:51], v[48:49]
	v_pk_add_f32 v[112:113], v[126:127], -1.0 op_sel_hi:[1,0]
	v_lshlrev_b32_e32 v46, 16, v47
	v_and_b32_e32 v47, 0xffff0000, v47
	v_pk_mul_f32 v[54:55], v[148:149], v[148:149]
	v_pk_fma_f32 v[112:113], v[30:31], v[112:113], 1.0 op_sel_hi:[1,1,0]
	v_pk_mul_f32 v[152:153], v[26:27], v[50:51]
	v_pk_add_f32 v[44:45], v[44:45], v[46:47] neg_lo:[0,1] neg_hi:[0,1]
	v_pk_mul_f32 v[150:151], v[50:51], v[112:113]
	v_pk_mul_f32 v[50:51], v[152:153], v[152:153]
	v_add_f32_e32 v54, v54, v55
	v_pk_fma_f32 v[44:45], v[18:19], v[44:45], v[46:47]
	v_add_f32_e32 v50, v54, v50
	v_pk_mul_f32 v[112:113], v[44:45], v[150:151]
	v_add_f32_e32 v50, v51, v50
	v_fmac_f32_e32 v154, v34, v112
	v_fmac_f32_e32 v154, v35, v113
	v_add_f32_dpp v50, v50, v50 quad_perm:[1,0,3,2] row_mask:0xf bank_mask:0xf bound_ctrl:1
	s_nop 1
	v_add_f32_dpp v50, v50, v50 quad_perm:[2,3,0,1] row_mask:0xf bank_mask:0xf bound_ctrl:1
	s_nop 1
	v_add_f32_dpp v58, v50, v50 row_half_mirror row_mask:0xf bank_mask:0xf bound_ctrl:1
	v_add_f32_dpp v50, v154, v154 quad_perm:[1,0,3,2] row_mask:0xf bank_mask:0xf bound_ctrl:1
	s_nop 0
	v_mov_b32_dpp v103, v58 row_mirror row_mask:0xf bank_mask:0xf bound_ctrl:1
	v_add_f32_dpp v50, v50, v50 quad_perm:[2,3,0,1] row_mask:0xf bank_mask:0xf bound_ctrl:1
	s_nop 1
	v_add_f32_dpp v50, v50, v50 row_half_mirror row_mask:0xf bank_mask:0xf bound_ctrl:1
	s_nop 1
	v_mov_b32_dpp v51, v50 row_mirror row_mask:0xf bank_mask:0xf bound_ctrl:1
	s_and_saveexec_b64 s[10:11], s[6:7]
	s_cbranch_execz .LBB0_203
	v_lshlrev_b64 v[54:55], 6, v[122:123]
	v_lshl_add_u64 v[54:55], v[98:99], 0, v[54:55]
	v_add_f32_e32 v50, v50, v51
	global_store_dword v[54:55], v50, off
.LBB0_203:
	s_or_b64 exec, exec, s[10:11]
	v_lshlrev_b32_e32 v50, 16, v36
	v_add_f32_e32 v50, v8, v50
	v_mul_f32_e32 v50, 0xbfb8aa3b, v50
	v_exp_f32_e32 v123, v50
	v_lshlrev_b32_e32 v112, 16, v116
	v_and_b32_e32 v113, 0xffff0000, v116
	v_pk_add_f32 v[110:111], v[110:111], v[112:113] neg_lo:[0,1] neg_hi:[0,1]
	v_add_f32_e32 v116, 1.0, v123
	v_rcp_f32_e32 v116, v116
	v_lshlrev_b32_e32 v50, 16, v117
	v_and_b32_e32 v51, 0xffff0000, v117
	v_and_b32_e32 v117, 0xffff0000, v36
	v_pk_fma_f32 v[110:111], v[4:5], v[110:111], v[112:113]
	v_lshlrev_b32_e32 v123, 16, v37
	v_and_b32_e32 v155, 0xffff0000, v37
	v_mul_f32_e32 v36, 0xbf1b4598, v116
	v_mul_f32_e32 v37, 0xbfb8aa3b, v110
	v_add_f32_e32 v116, v9, v117
	v_exp_f32_e32 v37, v37
	v_mul_f32_e32 v116, 0xbfb8aa3b, v116
	v_exp_f32_e32 v117, v116
	v_add_f32_e32 v123, v10, v123
	v_add_f32_e32 v37, 1.0, v37
	v_rcp_f32_e32 v116, v37
	v_add_f32_e32 v37, 1.0, v117
	v_mul_f32_e32 v117, 0xbfb8aa3b, v111
	v_mul_f32_e32 v123, 0xbfb8aa3b, v123
	v_exp_f32_e32 v117, v117
	v_exp_f32_e32 v123, v123
	v_rcp_f32_e32 v37, v37
	v_pk_add_f32 v[52:53], v[52:53], v[50:51] neg_lo:[0,1] neg_hi:[0,1]
	v_add_f32_e32 v117, 1.0, v117
	v_add_f32_e32 v123, 1.0, v123
	v_rcp_f32_e32 v117, v117
	v_rcp_f32_e32 v123, v123
	v_pk_fma_f32 v[52:53], v[6:7], v[52:53], v[50:51]
	v_mul_f32_e32 v37, 0xbf1b4598, v37
	v_pk_mul_f32 v[110:111], v[110:111], v[116:117]
	v_mul_f32_e32 v116, 0xbf1b4598, v123
	v_add_f32_e32 v117, v11, v155
	v_mul_f32_e32 v116, 0x3fb8aa3b, v116
	v_mul_f32_e32 v117, 0xbfb8aa3b, v117
	v_exp_f32_e32 v154, v116
	v_mul_f32_e32 v116, 0xbfb8aa3b, v52
	v_exp_f32_e32 v117, v117
	v_mul_f32_e32 v123, 0xbfb8aa3b, v53
	v_exp_f32_e32 v116, v116
	v_exp_f32_e32 v123, v123
	v_mul_f32_e32 v36, 0x3fb8aa3b, v36
	v_mul_f32_e32 v37, 0x3fb8aa3b, v37
	v_exp_f32_e32 v36, v36
	v_exp_f32_e32 v37, v37
	v_add_f32_e32 v117, 1.0, v117
	v_add_f32_e32 v116, 1.0, v116
	v_rcp_f32_e32 v155, v117
	v_add_f32_e32 v117, 1.0, v123
	v_rcp_f32_e32 v116, v116
	v_rcp_f32_e32 v117, v117
	v_add_f32_e32 v58, v58, v103
	v_max_f32_e32 v58, 0x179abe15, v58
	v_pk_add_f32 v[36:37], v[36:37], -1.0 op_sel_hi:[1,0]
	v_mul_f32_e32 v123, 0xbf1b4598, v155
	v_rsq_f32_e32 v58, v58
	v_pk_add_f32 v[36:37], v[36:37], 1.0 op_sel_hi:[1,0]
	v_mul_f32_e32 v123, 0x3fb8aa3b, v123
	v_pk_mul_f32 v[52:53], v[52:53], v[116:117]
	v_pk_mul_f32 v[116:117], v[118:119], v[36:37]
	v_exp_f32_e32 v155, v123
	v_rcp_f32_e32 v36, v116
	v_rcp_f32_e32 v37, v117
	v_pk_mul_f32 v[148:149], v[148:149], v[58:59] op_sel_hi:[1,0]
	v_pk_mul_f32 v[38:39], v[38:39], v[116:117]
	v_pk_mul_f32 v[178:179], v[118:119], v[148:149]
	v_pk_mul_f32 v[118:119], v[124:125], v[148:149]
	v_pk_mul_f32 v[148:149], v[152:153], v[58:59] op_sel_hi:[1,0]
	v_pk_mul_f32 v[124:125], v[118:119], v[36:37]
	v_pk_mul_f32 v[36:37], v[108:109], v[36:37]
	v_pk_add_f32 v[108:109], v[154:155], -1.0 op_sel_hi:[1,0]
	v_mad_i64_i32 v[122:123], s[10:11], v122, s23, v[56:57]
	v_pk_add_f32 v[108:109], v[108:109], 1.0 op_sel_hi:[1,0]
	v_lshlrev_b32_e32 v54, 16, v42
	v_pk_mul_f32 v[118:119], v[120:121], v[108:109]
	v_and_b32_e32 v55, 0xffff0000, v42
	v_rcp_f32_e32 v108, v118
	v_rcp_f32_e32 v109, v119
	v_pk_mul_f32 v[44:45], v[44:45], v[118:119]
	v_lshlrev_b32_e32 v42, 16, v43
	v_and_b32_e32 v43, 0xffff0000, v43
	v_pk_mul_f32 v[126:127], v[126:127], v[148:149]
	v_cvt_pk_bf16_f32 v38, v38, v39
	v_cvt_pk_bf16_f32 v39, v44, v45
	v_lshlrev_b64 v[44:45], 1, v[122:123]
	v_pk_add_f32 v[104:105], v[104:105], v[54:55] neg_lo:[0,1] neg_hi:[0,1]
	v_pk_add_f32 v[40:41], v[40:41], v[42:43] neg_lo:[0,1] neg_hi:[0,1]
	v_pk_mul_f32 v[126:127], v[126:127], v[108:109]
	v_pk_mul_f32 v[108:109], v[150:151], v[108:109]
	v_lshl_add_u64 v[122:123], s[74:75], 0, v[44:45]
	v_pk_fma_f32 v[104:105], v[0:1], v[104:105], v[54:55]
	v_pk_fma_f32 v[40:41], v[2:3], v[40:41], v[42:43]
	global_store_dwordx2 v[122:123], v[38:39], off
	v_cvt_pk_bf16_f32 v36, v36, v37
	v_cvt_pk_bf16_f32 v37, v108, v109
	v_lshl_add_u64 v[38:39], s[76:77], 0, v[44:45]
	v_pk_mul_f32 v[120:121], v[120:121], v[148:149]
	global_store_dwordx2 v[38:39], v[36:37], off
	v_cvt_pk_bf16_f32 v36, v104, v105
	v_cvt_pk_bf16_f32 v37, v40, v41
	v_lshl_add_u64 v[38:39], s[78:79], 0, v[44:45]
	global_store_dwordx2 v[38:39], v[36:37], off
	v_cvt_pk_bf16_f32 v36, v178, v179
	v_cvt_pk_bf16_f32 v37, v120, v121
	v_lshl_add_u64 v[38:39], s[80:81], 0, v[44:45]
	global_store_dwordx2 v[38:39], v[36:37], off
	v_cvt_pk_bf16_f32 v36, v124, v125
	v_cvt_pk_bf16_f32 v37, v126, v127
	v_lshl_add_u64 v[38:39], s[82:83], 0, v[44:45]
	global_store_dwordx2 v[38:39], v[36:37], off
	v_cvt_pk_bf16_f32 v36, v110, v111
	v_cvt_pk_bf16_f32 v37, v52, v53
	v_lshl_add_u64 v[38:39], s[84:85], 0, v[44:45]
	v_add_u32_e32 v122, 4, v102
	global_store_dwordx2 v[38:39], v[36:37], off
	v_mad_i64_i32 v[36:37], s[10:11], v122, s22, v[60:61]
	v_add_co_u32_e32 v36, vcc, s2, v36
	v_ashrrev_i32_e32 v123, 31, v122
	s_nop 0
	v_addc_co_u32_e32 v37, vcc, 0, v37, vcc
	s_waitcnt vmcnt(6)
	v_mov_b64_e32 v[44:45], v[234:235]
	v_mov_b64_e32 v[52:53], v[236:237]
	v_mov_b64_e32 v[40:41], v[238:239]
	v_mov_b64_e32 v[120:121], v[240:241]
	v_add_u32_e32 v246, 5, v102
	v_mad_i64_i32 v[242:243], s[26:27], v246, s22, v[60:61]
	global_load_dwordx2 v[234:235], v[242:243], off
	global_load_dwordx2 v[236:237], v[242:243], off offset:2048
	v_add_co_u32_e32 v244, vcc, s2, v242
	s_nop 1
	v_addc_co_u32_e32 v245, vcc, 0, v243, vcc
	global_load_dwordx2 v[238:239], v[244:245], off
	global_load_dwordx2 v[240:241], v[244:245], off offset:2048
	ds_read2st64_b64 v[36:39], v170 offset0:16 offset1:80
	s_waitcnt lgkmcnt(0)
	v_lshlrev_b32_e32 v58, 16, v38
	v_and_b32_e32 v38, 0xffff0000, v38
	v_add_f32_e32 v38, v13, v38
	v_mul_f32_e32 v38, 0xbfb8aa3b, v38
	v_lshlrev_b32_e32 v103, 16, v39
	v_and_b32_e32 v126, 0xffff0000, v39
	v_add_f32_e32 v39, v12, v58
	v_exp_f32_e32 v58, v38
	v_mul_f32_e32 v39, 0xbfb8aa3b, v39
	v_exp_f32_e32 v39, v39
	v_add_f32_e32 v58, 1.0, v58
	v_rcp_f32_e32 v125, v58
	v_add_f32_e32 v58, v14, v103
	v_mul_f32_e32 v58, 0xbfb8aa3b, v58
	v_add_f32_e32 v103, v15, v126
	v_exp_f32_e32 v58, v58
	v_mul_f32_e32 v103, 0xbfb8aa3b, v103
	v_exp_f32_e32 v103, v103
	v_add_f32_e32 v38, 1.0, v39
	v_add_f32_e32 v58, 1.0, v58
	v_rcp_f32_e32 v124, v38
	v_rcp_f32_e32 v148, v58
	v_add_f32_e32 v58, 1.0, v103
	v_rcp_f32_e32 v149, v58
	v_lshlrev_b32_e32 v108, 16, v44
	v_and_b32_e32 v109, 0xffff0000, v44
	v_lshlrev_b32_e32 v44, 16, v45
	v_and_b32_e32 v45, 0xffff0000, v45
	v_lshlrev_b32_e32 v110, 16, v52
	v_and_b32_e32 v111, 0xffff0000, v52
	v_lshlrev_b32_e32 v52, 16, v53
	v_and_b32_e32 v53, 0xffff0000, v53
	v_pk_add_f32 v[104:105], v[114:115], v[110:111] neg_lo:[0,1] neg_hi:[0,1]
	v_pk_add_f32 v[46:47], v[46:47], v[44:45] neg_lo:[0,1] neg_hi:[0,1]
	v_pk_add_f32 v[38:39], v[106:107], v[108:109] neg_lo:[0,1] neg_hi:[0,1]
	v_pk_fma_f32 v[104:105], v[20:21], v[104:105], v[110:111]
	v_pk_add_f32 v[106:107], v[124:125], -1.0 op_sel_hi:[1,0]
	v_pk_fma_f32 v[126:127], v[18:19], v[46:47], v[44:45]
	v_pk_add_f32 v[46:47], v[48:49], v[52:53] neg_lo:[0,1] neg_hi:[0,1]
	v_pk_fma_f32 v[106:107], v[28:29], v[106:107], 1.0 op_sel_hi:[1,1,0]
	v_pk_mul_f32 v[150:151], v[24:25], v[104:105]
	v_pk_fma_f32 v[46:47], v[22:23], v[46:47], v[52:53]
	v_pk_add_f32 v[48:49], v[148:149], -1.0 op_sel_hi:[1,0]
	v_pk_fma_f32 v[38:39], v[16:17], v[38:39], v[108:109]
	v_pk_mul_f32 v[106:107], v[104:105], v[106:107]
	v_pk_mul_f32 v[104:105], v[150:151], v[150:151]
	v_pk_fma_f32 v[48:49], v[30:31], v[48:49], 1.0 op_sel_hi:[1,1,0]
	v_pk_mul_f32 v[152:153], v[26:27], v[46:47]
	v_pk_mul_f32 v[114:115], v[38:39], v[106:107]
	v_pk_mul_f32 v[48:49], v[46:47], v[48:49]
	v_pk_mul_f32 v[46:47], v[152:153], v[152:153]
	v_add_f32_e32 v58, v104, v105
	v_fma_f32 v154, v32, v114, 0
	v_add_f32_e32 v46, v58, v46
	v_fmac_f32_e32 v154, v33, v115
	v_pk_mul_f32 v[114:115], v[126:127], v[48:49]
	v_add_f32_e32 v46, v47, v46
	v_fmac_f32_e32 v154, v34, v114
	v_fmac_f32_e32 v154, v35, v115
	v_add_f32_dpp v46, v46, v46 quad_perm:[1,0,3,2] row_mask:0xf bank_mask:0xf bound_ctrl:1
	s_nop 1
	v_add_f32_dpp v46, v46, v46 quad_perm:[2,3,0,1] row_mask:0xf bank_mask:0xf bound_ctrl:1
	s_nop 1
	v_add_f32_dpp v58, v46, v46 row_half_mirror row_mask:0xf bank_mask:0xf bound_ctrl:1
	v_add_f32_dpp v46, v154, v154 quad_perm:[1,0,3,2] row_mask:0xf bank_mask:0xf bound_ctrl:1
	s_nop 0
	v_mov_b32_dpp v103, v58 row_mirror row_mask:0xf bank_mask:0xf bound_ctrl:1
	v_add_f32_dpp v46, v46, v46 quad_perm:[2,3,0,1] row_mask:0xf bank_mask:0xf bound_ctrl:1
	s_nop 1
	v_add_f32_dpp v46, v46, v46 row_half_mirror row_mask:0xf bank_mask:0xf bound_ctrl:1
	s_nop 1
	v_mov_b32_dpp v47, v46 row_mirror row_mask:0xf bank_mask:0xf bound_ctrl:1
	s_and_saveexec_b64 s[10:11], s[6:7]
	s_cbranch_execz .LBB0_205
	v_lshlrev_b64 v[104:105], 6, v[122:123]
	v_lshl_add_u64 v[104:105], v[98:99], 0, v[104:105]
	v_add_f32_e32 v46, v46, v47
	global_store_dword v[104:105], v46, off
.LBB0_205:
	s_or_b64 exec, exec, s[10:11]
	v_lshlrev_b32_e32 v46, 16, v36
	v_add_f32_e32 v46, v8, v46
	v_mul_f32_e32 v46, 0xbfb8aa3b, v46
	v_exp_f32_e32 v123, v46
	v_lshlrev_b32_e32 v114, 16, v120
	v_and_b32_e32 v115, 0xffff0000, v120
	v_pk_add_f32 v[112:113], v[112:113], v[114:115] neg_lo:[0,1] neg_hi:[0,1]
	v_add_f32_e32 v120, 1.0, v123
	v_rcp_f32_e32 v120, v120
	v_lshlrev_b32_e32 v46, 16, v121
	v_and_b32_e32 v47, 0xffff0000, v121
	v_and_b32_e32 v121, 0xffff0000, v36
	v_pk_fma_f32 v[112:113], v[4:5], v[112:113], v[114:115]
	v_lshlrev_b32_e32 v123, 16, v37
	v_and_b32_e32 v155, 0xffff0000, v37
	v_mul_f32_e32 v36, 0xbf1b4598, v120
	v_mul_f32_e32 v37, 0xbfb8aa3b, v112
	v_add_f32_e32 v120, v9, v121
	v_exp_f32_e32 v37, v37
	v_mul_f32_e32 v120, 0xbfb8aa3b, v120
	v_exp_f32_e32 v121, v120
	v_add_f32_e32 v123, v10, v123
	v_add_f32_e32 v37, 1.0, v37
	v_rcp_f32_e32 v120, v37
	v_add_f32_e32 v37, 1.0, v121
	v_mul_f32_e32 v121, 0xbfb8aa3b, v113
	v_mul_f32_e32 v123, 0xbfb8aa3b, v123
	v_exp_f32_e32 v121, v121
	v_exp_f32_e32 v123, v123
	v_rcp_f32_e32 v37, v37
	v_pk_add_f32 v[50:51], v[50:51], v[46:47] neg_lo:[0,1] neg_hi:[0,1]
	v_add_f32_e32 v121, 1.0, v121
	v_add_f32_e32 v123, 1.0, v123
	v_rcp_f32_e32 v121, v121
	v_rcp_f32_e32 v123, v123
	v_pk_fma_f32 v[50:51], v[6:7], v[50:51], v[46:47]
	v_mul_f32_e32 v37, 0xbf1b4598, v37
	v_pk_mul_f32 v[112:113], v[112:113], v[120:121]
	v_mul_f32_e32 v120, 0xbf1b4598, v123
	v_add_f32_e32 v121, v11, v155
	v_mul_f32_e32 v120, 0x3fb8aa3b, v120
	v_mul_f32_e32 v121, 0xbfb8aa3b, v121
	v_exp_f32_e32 v154, v120
	v_mul_f32_e32 v120, 0xbfb8aa3b, v50
	v_exp_f32_e32 v121, v121
	v_mul_f32_e32 v123, 0xbfb8aa3b, v51
	v_exp_f32_e32 v120, v120
	v_exp_f32_e32 v123, v123
	v_mul_f32_e32 v36, 0x3fb8aa3b, v36
	v_mul_f32_e32 v37, 0x3fb8aa3b, v37
	v_exp_f32_e32 v36, v36
	v_exp_f32_e32 v37, v37
	v_add_f32_e32 v121, 1.0, v121
	v_add_f32_e32 v120, 1.0, v120
	v_rcp_f32_e32 v155, v121
	v_add_f32_e32 v121, 1.0, v123
	v_rcp_f32_e32 v120, v120
	v_rcp_f32_e32 v121, v121
	v_add_f32_e32 v58, v58, v103
	v_max_f32_e32 v58, 0x179abe15, v58
	v_pk_add_f32 v[36:37], v[36:37], -1.0 op_sel_hi:[1,0]
	v_mul_f32_e32 v123, 0xbf1b4598, v155
	v_rsq_f32_e32 v58, v58
	v_pk_add_f32 v[36:37], v[36:37], 1.0 op_sel_hi:[1,0]
	v_mul_f32_e32 v123, 0x3fb8aa3b, v123
	v_pk_mul_f32 v[50:51], v[50:51], v[120:121]
	v_pk_mul_f32 v[120:121], v[116:117], v[36:37]
	v_exp_f32_e32 v155, v123
	v_rcp_f32_e32 v36, v120
	v_rcp_f32_e32 v37, v121
	v_pk_mul_f32 v[150:151], v[150:151], v[58:59] op_sel_hi:[1,0]
	v_lshlrev_b32_e32 v104, 16, v40
	v_pk_mul_f32 v[178:179], v[116:117], v[150:151]
	v_pk_mul_f32 v[116:117], v[124:125], v[150:151]
	v_pk_mul_f32 v[150:151], v[152:153], v[58:59] op_sel_hi:[1,0]
	v_pk_mul_f32 v[124:125], v[116:117], v[36:37]
	v_pk_mul_f32 v[36:37], v[106:107], v[36:37]
	v_pk_add_f32 v[106:107], v[154:155], -1.0 op_sel_hi:[1,0]
	v_pk_mul_f32 v[148:149], v[148:149], v[150:151]
	v_pk_add_f32 v[106:107], v[106:107], 1.0 op_sel_hi:[1,0]
	v_and_b32_e32 v105, 0xffff0000, v40
	v_pk_mul_f32 v[116:117], v[118:119], v[106:107]
	v_lshlrev_b32_e32 v40, 16, v41
	v_rcp_f32_e32 v106, v116
	v_rcp_f32_e32 v107, v117
	v_and_b32_e32 v41, 0xffff0000, v41
	v_pk_mul_f32 v[38:39], v[38:39], v[120:121]
	v_pk_mul_f32 v[126:127], v[126:127], v[116:117]
	v_pk_mul_f32 v[148:149], v[148:149], v[106:107]
	v_pk_mul_f32 v[48:49], v[48:49], v[106:107]
	v_mad_i64_i32 v[106:107], s[10:11], v122, s23, v[56:57]
	v_lshlrev_b64 v[106:107], 1, v[106:107]
	v_pk_add_f32 v[54:55], v[54:55], v[104:105] neg_lo:[0,1] neg_hi:[0,1]
	v_pk_add_f32 v[42:43], v[42:43], v[40:41] neg_lo:[0,1] neg_hi:[0,1]
	v_cvt_pk_bf16_f32 v38, v38, v39
	v_cvt_pk_bf16_f32 v39, v126, v127
	v_lshl_add_u64 v[122:123], s[74:75], 0, v[106:107]
	v_pk_fma_f32 v[54:55], v[0:1], v[54:55], v[104:105]
	v_pk_fma_f32 v[42:43], v[2:3], v[42:43], v[40:41]
	global_store_dwordx2 v[122:123], v[38:39], off
	v_cvt_pk_bf16_f32 v36, v36, v37
	v_cvt_pk_bf16_f32 v37, v48, v49
	v_lshl_add_u64 v[38:39], s[76:77], 0, v[106:107]
	v_pk_mul_f32 v[118:119], v[118:119], v[150:151]
	global_store_dwordx2 v[38:39], v[36:37], off
	v_cvt_pk_bf16_f32 v36, v54, v55
	v_cvt_pk_bf16_f32 v37, v42, v43
	v_lshl_add_u64 v[38:39], s[78:79], 0, v[106:107]
	global_store_dwordx2 v[38:39], v[36:37], off
	v_cvt_pk_bf16_f32 v36, v178, v179
	v_cvt_pk_bf16_f32 v37, v118, v119
	v_lshl_add_u64 v[38:39], s[80:81], 0, v[106:107]
	global_store_dwordx2 v[38:39], v[36:37], off
	v_cvt_pk_bf16_f32 v36, v124, v125
	v_cvt_pk_bf16_f32 v37, v148, v149
	v_lshl_add_u64 v[38:39], s[82:83], 0, v[106:107]
	global_store_dwordx2 v[38:39], v[36:37], off
	v_cvt_pk_bf16_f32 v36, v112, v113
	v_cvt_pk_bf16_f32 v37, v50, v51
	v_lshl_add_u64 v[38:39], s[84:85], 0, v[106:107]
	v_add_u32_e32 v122, 5, v102
	global_store_dwordx2 v[38:39], v[36:37], off
	v_mad_i64_i32 v[36:37], s[10:11], v122, s22, v[60:61]
	v_add_co_u32_e32 v36, vcc, s2, v36
	v_ashrrev_i32_e32 v123, 31, v122
	s_nop 0
	v_addc_co_u32_e32 v37, vcc, 0, v37, vcc
	s_waitcnt vmcnt(6)
	v_mov_b64_e32 v[48:49], v[234:235]
	v_mov_b64_e32 v[50:51], v[236:237]
	v_mov_b64_e32 v[42:43], v[238:239]
	v_mov_b64_e32 v[118:119], v[240:241]
	v_add_u32_e32 v246, 6, v102
	v_mad_i64_i32 v[242:243], s[26:27], v246, s22, v[60:61]
	global_load_dwordx2 v[234:235], v[242:243], off
	global_load_dwordx2 v[236:237], v[242:243], off offset:2048
	v_add_co_u32_e32 v244, vcc, s2, v242
	s_nop 1
	v_addc_co_u32_e32 v245, vcc, 0, v243, vcc
	global_load_dwordx2 v[238:239], v[244:245], off
	global_load_dwordx2 v[240:241], v[244:245], off offset:2048
	ds_read2st64_b64 v[36:39], v171 offset0:16 offset1:80
	s_waitcnt lgkmcnt(0)
	v_lshlrev_b32_e32 v54, 16, v38
	v_and_b32_e32 v38, 0xffff0000, v38
	v_lshlrev_b32_e32 v58, 16, v39
	v_and_b32_e32 v103, 0xffff0000, v39
	v_add_f32_e32 v39, v12, v54
	v_add_f32_e32 v38, v13, v38
	v_mul_f32_e32 v39, 0xbfb8aa3b, v39
	v_mul_f32_e32 v38, 0xbfb8aa3b, v38
	v_exp_f32_e32 v39, v39
	v_exp_f32_e32 v54, v38
	v_add_f32_e32 v58, v14, v58
	v_mul_f32_e32 v58, 0xbfb8aa3b, v58
	v_add_f32_e32 v103, v15, v103
	v_add_f32_e32 v38, 1.0, v39
	v_add_f32_e32 v54, 1.0, v54
	v_exp_f32_e32 v58, v58
	v_mul_f32_e32 v103, 0xbfb8aa3b, v103
	v_rcp_f32_e32 v124, v38
	v_rcp_f32_e32 v125, v54
	v_exp_f32_e32 v103, v103
	v_add_f32_e32 v58, 1.0, v58
	v_rcp_f32_e32 v126, v58
	v_add_f32_e32 v58, 1.0, v103
	v_rcp_f32_e32 v127, v58
	v_lshlrev_b32_e32 v106, 16, v48
	v_and_b32_e32 v107, 0xffff0000, v48
	v_lshlrev_b32_e32 v112, 16, v50
	v_and_b32_e32 v113, 0xffff0000, v50
	v_pk_add_f32 v[38:39], v[108:109], v[106:107] neg_lo:[0,1] neg_hi:[0,1]
	v_pk_add_f32 v[54:55], v[110:111], v[112:113] neg_lo:[0,1] neg_hi:[0,1]
	v_pk_add_f32 v[108:109], v[124:125], -1.0 op_sel_hi:[1,0]
	v_pk_fma_f32 v[54:55], v[20:21], v[54:55], v[112:113]
	v_pk_fma_f32 v[108:109], v[28:29], v[108:109], 1.0 op_sel_hi:[1,1,0]
	v_pk_fma_f32 v[38:39], v[16:17], v[38:39], v[106:107]
	v_pk_mul_f32 v[108:109], v[54:55], v[108:109]
	v_lshlrev_b32_e32 v50, 16, v51
	v_and_b32_e32 v51, 0xffff0000, v51
	v_pk_mul_f32 v[110:111], v[38:39], v[108:109]
	v_pk_add_f32 v[52:53], v[52:53], v[50:51] neg_lo:[0,1] neg_hi:[0,1]
	v_fma_f32 v154, v32, v110, 0
	v_pk_mul_f32 v[148:149], v[24:25], v[54:55]
	v_fmac_f32_e32 v154, v33, v111
	v_pk_fma_f32 v[52:53], v[22:23], v[52:53], v[50:51]
	v_pk_add_f32 v[110:111], v[126:127], -1.0 op_sel_hi:[1,0]
	v_lshlrev_b32_e32 v48, 16, v49
	v_and_b32_e32 v49, 0xffff0000, v49
	v_pk_mul_f32 v[54:55], v[148:149], v[148:149]
	v_pk_fma_f32 v[110:111], v[30:31], v[110:111], 1.0 op_sel_hi:[1,1,0]
	v_pk_mul_f32 v[152:153], v[26:27], v[52:53]
	v_pk_add_f32 v[44:45], v[44:45], v[48:49] neg_lo:[0,1] neg_hi:[0,1]
	v_pk_mul_f32 v[150:151], v[52:53], v[110:111]
	v_pk_mul_f32 v[52:53], v[152:153], v[152:153]
	v_add_f32_e32 v54, v54, v55
	v_pk_fma_f32 v[44:45], v[18:19], v[44:45], v[48:49]
	v_add_f32_e32 v52, v54, v52
	v_pk_mul_f32 v[110:111], v[44:45], v[150:151]
	v_add_f32_e32 v52, v53, v52
	v_fmac_f32_e32 v154, v34, v110
	v_fmac_f32_e32 v154, v35, v111
	v_add_f32_dpp v52, v52, v52 quad_perm:[1,0,3,2] row_mask:0xf bank_mask:0xf bound_ctrl:1
	s_nop 1
	v_add_f32_dpp v52, v52, v52 quad_perm:[2,3,0,1] row_mask:0xf bank_mask:0xf bound_ctrl:1
	s_nop 1
	v_add_f32_dpp v58, v52, v52 row_half_mirror row_mask:0xf bank_mask:0xf bound_ctrl:1
	v_add_f32_dpp v52, v154, v154 quad_perm:[1,0,3,2] row_mask:0xf bank_mask:0xf bound_ctrl:1
	s_nop 0
	v_mov_b32_dpp v103, v58 row_mirror row_mask:0xf bank_mask:0xf bound_ctrl:1
	v_add_f32_dpp v52, v52, v52 quad_perm:[2,3,0,1] row_mask:0xf bank_mask:0xf bound_ctrl:1
	s_nop 1
	v_add_f32_dpp v52, v52, v52 row_half_mirror row_mask:0xf bank_mask:0xf bound_ctrl:1
	s_nop 1
	v_mov_b32_dpp v53, v52 row_mirror row_mask:0xf bank_mask:0xf bound_ctrl:1
	s_and_saveexec_b64 s[10:11], s[6:7]
	s_cbranch_execz .LBB0_207
	v_lshlrev_b64 v[54:55], 6, v[122:123]
	v_lshl_add_u64 v[54:55], v[98:99], 0, v[54:55]
	v_add_f32_e32 v52, v52, v53
	global_store_dword v[54:55], v52, off
.LBB0_207:
	s_or_b64 exec, exec, s[10:11]
	v_lshlrev_b32_e32 v52, 16, v36
	v_add_f32_e32 v52, v8, v52
	v_mul_f32_e32 v52, 0xbfb8aa3b, v52
	v_exp_f32_e32 v123, v52
	v_lshlrev_b32_e32 v110, 16, v118
	v_and_b32_e32 v111, 0xffff0000, v118
	v_pk_add_f32 v[114:115], v[114:115], v[110:111] neg_lo:[0,1] neg_hi:[0,1]
	v_add_f32_e32 v118, 1.0, v123
	v_rcp_f32_e32 v118, v118
	v_lshlrev_b32_e32 v52, 16, v119
	v_and_b32_e32 v53, 0xffff0000, v119
	v_and_b32_e32 v119, 0xffff0000, v36
	v_pk_fma_f32 v[114:115], v[4:5], v[114:115], v[110:111]
	v_lshlrev_b32_e32 v123, 16, v37
	v_and_b32_e32 v155, 0xffff0000, v37
	v_mul_f32_e32 v36, 0xbf1b4598, v118
	v_mul_f32_e32 v37, 0xbfb8aa3b, v114
	v_add_f32_e32 v118, v9, v119
	v_exp_f32_e32 v37, v37
	v_mul_f32_e32 v118, 0xbfb8aa3b, v118
	v_exp_f32_e32 v119, v118
	v_add_f32_e32 v123, v10, v123
	v_add_f32_e32 v37, 1.0, v37
	v_rcp_f32_e32 v118, v37
	v_add_f32_e32 v37, 1.0, v119
	v_mul_f32_e32 v119, 0xbfb8aa3b, v115
	v_mul_f32_e32 v123, 0xbfb8aa3b, v123
	v_exp_f32_e32 v119, v119
	v_exp_f32_e32 v123, v123
	v_rcp_f32_e32 v37, v37
	v_pk_add_f32 v[46:47], v[46:47], v[52:53] neg_lo:[0,1] neg_hi:[0,1]
	v_add_f32_e32 v119, 1.0, v119
	v_add_f32_e32 v123, 1.0, v123
	v_rcp_f32_e32 v119, v119
	v_rcp_f32_e32 v123, v123
	v_pk_fma_f32 v[46:47], v[6:7], v[46:47], v[52:53]
	v_mul_f32_e32 v37, 0xbf1b4598, v37
	v_pk_mul_f32 v[114:115], v[114:115], v[118:119]
	v_mul_f32_e32 v118, 0xbf1b4598, v123
	v_add_f32_e32 v119, v11, v155
	v_mul_f32_e32 v118, 0x3fb8aa3b, v118
	v_mul_f32_e32 v119, 0xbfb8aa3b, v119
	v_exp_f32_e32 v154, v118
	v_mul_f32_e32 v118, 0xbfb8aa3b, v46
	v_exp_f32_e32 v119, v119
	v_mul_f32_e32 v123, 0xbfb8aa3b, v47
	v_exp_f32_e32 v118, v118
	v_exp_f32_e32 v123, v123
	v_mul_f32_e32 v36, 0x3fb8aa3b, v36
	v_mul_f32_e32 v37, 0x3fb8aa3b, v37
	v_exp_f32_e32 v36, v36
	v_exp_f32_e32 v37, v37
	v_add_f32_e32 v119, 1.0, v119
	v_add_f32_e32 v118, 1.0, v118
	v_rcp_f32_e32 v155, v119
	v_add_f32_e32 v119, 1.0, v123
	v_rcp_f32_e32 v118, v118
	v_rcp_f32_e32 v119, v119
	v_add_f32_e32 v58, v58, v103
	v_max_f32_e32 v58, 0x179abe15, v58
	v_pk_add_f32 v[36:37], v[36:37], -1.0 op_sel_hi:[1,0]
	v_mul_f32_e32 v123, 0xbf1b4598, v155
	v_rsq_f32_e32 v58, v58
	v_pk_add_f32 v[36:37], v[36:37], 1.0 op_sel_hi:[1,0]
	v_mul_f32_e32 v123, 0x3fb8aa3b, v123
	v_pk_mul_f32 v[46:47], v[46:47], v[118:119]
	v_pk_mul_f32 v[118:119], v[120:121], v[36:37]
	v_exp_f32_e32 v155, v123
	v_rcp_f32_e32 v36, v118
	v_rcp_f32_e32 v37, v119
	v_pk_mul_f32 v[148:149], v[148:149], v[58:59] op_sel_hi:[1,0]
	v_pk_mul_f32 v[38:39], v[38:39], v[118:119]
	v_pk_mul_f32 v[178:179], v[120:121], v[148:149]
	v_pk_mul_f32 v[120:121], v[124:125], v[148:149]
	v_pk_mul_f32 v[148:149], v[152:153], v[58:59] op_sel_hi:[1,0]
	v_pk_mul_f32 v[124:125], v[120:121], v[36:37]
	v_pk_mul_f32 v[36:37], v[108:109], v[36:37]
	v_pk_add_f32 v[108:109], v[154:155], -1.0 op_sel_hi:[1,0]
	v_mad_i64_i32 v[122:123], s[10:11], v122, s23, v[56:57]
	v_pk_add_f32 v[108:109], v[108:109], 1.0 op_sel_hi:[1,0]
	v_lshlrev_b32_e32 v54, 16, v42
	v_pk_mul_f32 v[120:121], v[116:117], v[108:109]
	v_and_b32_e32 v55, 0xffff0000, v42
	v_rcp_f32_e32 v108, v120
	v_rcp_f32_e32 v109, v121
	v_pk_mul_f32 v[44:45], v[44:45], v[120:121]
	v_lshlrev_b32_e32 v42, 16, v43
	v_and_b32_e32 v43, 0xffff0000, v43
	v_pk_mul_f32 v[126:127], v[126:127], v[148:149]
	v_cvt_pk_bf16_f32 v38, v38, v39
	v_cvt_pk_bf16_f32 v39, v44, v45
	v_lshlrev_b64 v[44:45], 1, v[122:123]
	v_pk_add_f32 v[104:105], v[104:105], v[54:55] neg_lo:[0,1] neg_hi:[0,1]
	v_pk_add_f32 v[40:41], v[40:41], v[42:43] neg_lo:[0,1] neg_hi:[0,1]
	v_pk_mul_f32 v[126:127], v[126:127], v[108:109]
	v_pk_mul_f32 v[108:109], v[150:151], v[108:109]
	v_lshl_add_u64 v[122:123], s[74:75], 0, v[44:45]
	v_pk_fma_f32 v[104:105], v[0:1], v[104:105], v[54:55]
	v_pk_fma_f32 v[40:41], v[2:3], v[40:41], v[42:43]
	global_store_dwordx2 v[122:123], v[38:39], off
	v_cvt_pk_bf16_f32 v36, v36, v37
	v_cvt_pk_bf16_f32 v37, v108, v109
	v_lshl_add_u64 v[38:39], s[76:77], 0, v[44:45]
	v_pk_mul_f32 v[116:117], v[116:117], v[148:149]
	global_store_dwordx2 v[38:39], v[36:37], off
	v_cvt_pk_bf16_f32 v36, v104, v105
	v_cvt_pk_bf16_f32 v37, v40, v41
	v_lshl_add_u64 v[38:39], s[78:79], 0, v[44:45]
	global_store_dwordx2 v[38:39], v[36:37], off
	v_cvt_pk_bf16_f32 v36, v178, v179
	v_cvt_pk_bf16_f32 v37, v116, v117
	v_lshl_add_u64 v[38:39], s[80:81], 0, v[44:45]
	global_store_dwordx2 v[38:39], v[36:37], off
	v_cvt_pk_bf16_f32 v36, v124, v125
	v_cvt_pk_bf16_f32 v37, v126, v127
	v_lshl_add_u64 v[38:39], s[82:83], 0, v[44:45]
	global_store_dwordx2 v[38:39], v[36:37], off
	v_cvt_pk_bf16_f32 v36, v114, v115
	v_cvt_pk_bf16_f32 v37, v46, v47
	v_lshl_add_u64 v[38:39], s[84:85], 0, v[44:45]
	v_add_u32_e32 v116, 6, v102
	global_store_dwordx2 v[38:39], v[36:37], off
	v_mad_i64_i32 v[36:37], s[10:11], v116, s22, v[60:61]
	v_add_co_u32_e32 v36, vcc, s2, v36
	v_ashrrev_i32_e32 v117, 31, v116
	s_nop 0
	v_addc_co_u32_e32 v37, vcc, 0, v37, vcc
	s_waitcnt vmcnt(6)
	v_mov_b64_e32 v[44:45], v[234:235]
	v_mov_b64_e32 v[46:47], v[236:237]
	v_mov_b64_e32 v[40:41], v[238:239]
	v_mov_b64_e32 v[152:153], v[240:241]
	v_add_u32_e32 v246, 7, v102
	v_mad_i64_i32 v[242:243], s[26:27], v246, s22, v[60:61]
	global_load_dwordx2 v[234:235], v[242:243], off
	global_load_dwordx2 v[236:237], v[242:243], off offset:2048
	v_add_co_u32_e32 v244, vcc, s2, v242
	s_nop 1
	v_addc_co_u32_e32 v245, vcc, 0, v243, vcc
	global_load_dwordx2 v[238:239], v[244:245], off
	global_load_dwordx2 v[240:241], v[244:245], off offset:2048
	ds_read2st64_b64 v[36:39], v172 offset0:16 offset1:80
	s_waitcnt lgkmcnt(0)
	v_lshlrev_b32_e32 v58, 16, v38
	v_and_b32_e32 v38, 0xffff0000, v38
	v_add_f32_e32 v38, v13, v38
	v_mul_f32_e32 v38, 0xbfb8aa3b, v38
	v_lshlrev_b32_e32 v103, 16, v39
	v_and_b32_e32 v124, 0xffff0000, v39
	v_add_f32_e32 v39, v12, v58
	v_exp_f32_e32 v58, v38
	v_mul_f32_e32 v39, 0xbfb8aa3b, v39
	v_exp_f32_e32 v39, v39
	v_add_f32_e32 v58, 1.0, v58
	v_rcp_f32_e32 v123, v58
	v_add_f32_e32 v58, v14, v103
	v_mul_f32_e32 v58, 0xbfb8aa3b, v58
	v_add_f32_e32 v103, v15, v124
	v_add_f32_e32 v38, 1.0, v39
	v_exp_f32_e32 v58, v58
	v_mul_f32_e32 v103, 0xbfb8aa3b, v103
	v_rcp_f32_e32 v122, v38
	v_exp_f32_e32 v103, v103
	v_add_f32_e32 v58, 1.0, v58
	v_rcp_f32_e32 v124, v58
	v_add_f32_e32 v58, 1.0, v103
	v_rcp_f32_e32 v125, v58
	v_lshlrev_b32_e32 v108, 16, v44
	v_and_b32_e32 v109, 0xffff0000, v44
	v_lshlrev_b32_e32 v114, 16, v46
	v_and_b32_e32 v115, 0xffff0000, v46
	v_pk_add_f32 v[38:39], v[106:107], v[108:109] neg_lo:[0,1] neg_hi:[0,1]
	v_pk_add_f32 v[104:105], v[112:113], v[114:115] neg_lo:[0,1] neg_hi:[0,1]
	v_pk_add_f32 v[106:107], v[122:123], -1.0 op_sel_hi:[1,0]
	v_pk_fma_f32 v[104:105], v[20:21], v[104:105], v[114:115]
	v_pk_fma_f32 v[106:107], v[28:29], v[106:107], 1.0 op_sel_hi:[1,1,0]
	v_pk_fma_f32 v[38:39], v[16:17], v[38:39], v[108:109]
	v_pk_mul_f32 v[106:107], v[104:105], v[106:107]
	v_lshlrev_b32_e32 v44, 16, v45
	v_and_b32_e32 v45, 0xffff0000, v45
	v_pk_mul_f32 v[112:113], v[38:39], v[106:107]
	v_lshlrev_b32_e32 v46, 16, v47
	v_and_b32_e32 v47, 0xffff0000, v47
	v_fma_f32 v154, v32, v112, 0
	v_pk_add_f32 v[48:49], v[48:49], v[44:45] neg_lo:[0,1] neg_hi:[0,1]
	v_fmac_f32_e32 v154, v33, v113
	v_pk_fma_f32 v[112:113], v[18:19], v[48:49], v[44:45]
	v_pk_add_f32 v[48:49], v[50:51], v[46:47] neg_lo:[0,1] neg_hi:[0,1]
	v_pk_add_f32 v[50:51], v[124:125], -1.0 op_sel_hi:[1,0]
	v_pk_fma_f32 v[48:49], v[22:23], v[48:49], v[46:47]
	v_pk_fma_f32 v[50:51], v[30:31], v[50:51], 1.0 op_sel_hi:[1,1,0]
	v_pk_mul_f32 v[126:127], v[24:25], v[104:105]
	v_pk_mul_f32 v[148:149], v[48:49], v[50:51]
	v_pk_mul_f32 v[104:105], v[126:127], v[126:127]
	v_pk_mul_f32 v[50:51], v[112:113], v[148:149]
	v_pk_mul_f32 v[150:151], v[26:27], v[48:49]
	v_fmac_f32_e32 v154, v34, v50
	v_pk_mul_f32 v[48:49], v[150:151], v[150:151]
	v_add_f32_e32 v50, v104, v105
	v_add_f32_e32 v48, v50, v48
	v_add_f32_e32 v48, v49, v48
	v_fmac_f32_e32 v154, v35, v51
	s_nop 0
	v_add_f32_dpp v48, v48, v48 quad_perm:[1,0,3,2] row_mask:0xf bank_mask:0xf bound_ctrl:1
	s_nop 1
	v_add_f32_dpp v48, v48, v48 quad_perm:[2,3,0,1] row_mask:0xf bank_mask:0xf bound_ctrl:1
	s_nop 1
	v_add_f32_dpp v58, v48, v48 row_half_mirror row_mask:0xf bank_mask:0xf bound_ctrl:1
	v_add_f32_dpp v48, v154, v154 quad_perm:[1,0,3,2] row_mask:0xf bank_mask:0xf bound_ctrl:1
	s_nop 0
	v_mov_b32_dpp v103, v58 row_mirror row_mask:0xf bank_mask:0xf bound_ctrl:1
	v_add_f32_dpp v48, v48, v48 quad_perm:[2,3,0,1] row_mask:0xf bank_mask:0xf bound_ctrl:1
	s_nop 1
	v_add_f32_dpp v48, v48, v48 row_half_mirror row_mask:0xf bank_mask:0xf bound_ctrl:1
	s_nop 1
	v_mov_b32_dpp v49, v48 row_mirror row_mask:0xf bank_mask:0xf bound_ctrl:1
	s_and_saveexec_b64 s[10:11], s[6:7]
	s_cbranch_execz .LBB0_209
	v_lshlrev_b64 v[50:51], 6, v[116:117]
	v_lshl_add_u64 v[50:51], v[98:99], 0, v[50:51]
	v_add_f32_e32 v48, v48, v49
	global_store_dword v[50:51], v48, off
.LBB0_209:
	s_or_b64 exec, exec, s[10:11]
	v_lshlrev_b32_e32 v48, 16, v36
	v_add_f32_e32 v48, v8, v48
	v_mul_f32_e32 v48, 0xbfb8aa3b, v48
	v_exp_f32_e32 v117, v48
	v_lshlrev_b32_e32 v104, 16, v152
	v_and_b32_e32 v105, 0xffff0000, v152
	v_pk_add_f32 v[110:111], v[110:111], v[104:105] neg_lo:[0,1] neg_hi:[0,1]
	v_add_f32_e32 v117, 1.0, v117
	v_rcp_f32_e32 v117, v117
	v_and_b32_e32 v152, 0xffff0000, v36
	v_pk_fma_f32 v[110:111], v[4:5], v[110:111], v[104:105]
	v_lshlrev_b32_e32 v48, 16, v153
	v_and_b32_e32 v49, 0xffff0000, v153
	v_lshlrev_b32_e32 v153, 16, v37
	v_and_b32_e32 v178, 0xffff0000, v37
	v_mul_f32_e32 v36, 0xbf1b4598, v117
	v_mul_f32_e32 v37, 0xbfb8aa3b, v110
	v_add_f32_e32 v117, v9, v152
	v_exp_f32_e32 v37, v37
	v_mul_f32_e32 v117, 0xbfb8aa3b, v117
	v_exp_f32_e32 v117, v117
	v_add_f32_e32 v153, v10, v153
	v_add_f32_e32 v37, 1.0, v37
	v_rcp_f32_e32 v152, v37
	v_add_f32_e32 v37, 1.0, v117
	v_mul_f32_e32 v117, 0xbfb8aa3b, v111
	v_exp_f32_e32 v117, v117
	v_mul_f32_e32 v153, 0xbfb8aa3b, v153
	v_exp_f32_e32 v154, v153
	v_lshlrev_b32_e32 v50, 16, v40
	v_add_f32_e32 v117, 1.0, v117
	v_rcp_f32_e32 v153, v117
	v_add_f32_e32 v117, 1.0, v154
	v_rcp_f32_e32 v117, v117
	v_and_b32_e32 v51, 0xffff0000, v40
	v_lshlrev_b32_e32 v40, 16, v41
	v_and_b32_e32 v41, 0xffff0000, v41
	v_pk_add_f32 v[42:43], v[42:43], v[40:41] neg_lo:[0,1] neg_hi:[0,1]
	v_mul_f32_e32 v117, 0xbf1b4598, v117
	v_pk_fma_f32 v[154:155], v[2:3], v[42:43], v[40:41]
	v_pk_add_f32 v[42:43], v[52:53], v[48:49] neg_lo:[0,1] neg_hi:[0,1]
	v_add_f32_e32 v53, v11, v178
	v_mul_f32_e32 v117, 0x3fb8aa3b, v117
	v_pk_fma_f32 v[42:43], v[6:7], v[42:43], v[48:49]
	v_mul_f32_e32 v53, 0xbfb8aa3b, v53
	v_pk_mul_f32 v[110:111], v[110:111], v[152:153]
	v_exp_f32_e32 v152, v117
	v_mul_f32_e32 v52, 0xbfb8aa3b, v42
	v_exp_f32_e32 v53, v53
	v_mul_f32_e32 v117, 0xbfb8aa3b, v43
	v_rcp_f32_e32 v37, v37
	v_exp_f32_e32 v52, v52
	v_exp_f32_e32 v117, v117
	v_add_f32_e32 v53, 1.0, v53
	v_mul_f32_e32 v37, 0xbf1b4598, v37
	v_add_f32_e32 v52, 1.0, v52
	v_rcp_f32_e32 v153, v53
	v_add_f32_e32 v53, 1.0, v117
	v_mul_f32_e32 v36, 0x3fb8aa3b, v36
	v_mul_f32_e32 v37, 0x3fb8aa3b, v37
	v_rcp_f32_e32 v52, v52
	v_rcp_f32_e32 v53, v53
	v_exp_f32_e32 v36, v36
	v_exp_f32_e32 v37, v37
	v_mul_f32_e32 v117, 0xbf1b4598, v153
	v_pk_mul_f32 v[178:179], v[42:43], v[52:53]
	v_add_f32_e32 v42, v58, v103
	v_max_f32_e32 v42, 0x179abe15, v42
	v_pk_add_f32 v[36:37], v[36:37], -1.0 op_sel_hi:[1,0]
	v_rsq_f32_e32 v58, v42
	v_pk_add_f32 v[36:37], v[36:37], 1.0 op_sel_hi:[1,0]
	v_mul_f32_e32 v117, 0x3fb8aa3b, v117
	v_pk_mul_f32 v[42:43], v[118:119], v[36:37]
	v_exp_f32_e32 v153, v117
	v_rcp_f32_e32 v36, v42
	v_rcp_f32_e32 v37, v43
	v_pk_mul_f32 v[52:53], v[126:127], v[58:59] op_sel_hi:[1,0]
	v_pk_mul_f32 v[38:39], v[38:39], v[42:43]
	v_pk_mul_f32 v[118:119], v[118:119], v[52:53]
	v_pk_mul_f32 v[52:53], v[122:123], v[52:53]
	v_pk_mul_f32 v[126:127], v[150:151], v[58:59] op_sel_hi:[1,0]
	v_pk_mul_f32 v[122:123], v[52:53], v[36:37]
	v_pk_add_f32 v[52:53], v[152:153], -1.0 op_sel_hi:[1,0]
	v_pk_mul_f32 v[36:37], v[106:107], v[36:37]
	v_pk_add_f32 v[52:53], v[52:53], 1.0 op_sel_hi:[1,0]
	v_mad_i64_i32 v[116:117], s[10:11], v116, s23, v[56:57]
	v_pk_mul_f32 v[52:53], v[120:121], v[52:53]
	v_pk_mul_f32 v[124:125], v[124:125], v[126:127]
	v_rcp_f32_e32 v106, v52
	v_rcp_f32_e32 v107, v53
	v_pk_mul_f32 v[112:113], v[112:113], v[52:53]
	v_cvt_pk_bf16_f32 v38, v38, v39
	v_cvt_pk_bf16_f32 v39, v112, v113
	v_lshlrev_b64 v[112:113], 1, v[116:117]
	v_pk_add_f32 v[54:55], v[54:55], v[50:51] neg_lo:[0,1] neg_hi:[0,1]
	v_pk_mul_f32 v[124:125], v[124:125], v[106:107]
	v_pk_mul_f32 v[106:107], v[148:149], v[106:107]
	v_lshl_add_u64 v[116:117], s[74:75], 0, v[112:113]
	v_pk_fma_f32 v[54:55], v[0:1], v[54:55], v[50:51]
	global_store_dwordx2 v[116:117], v[38:39], off
	v_cvt_pk_bf16_f32 v36, v36, v37
	v_cvt_pk_bf16_f32 v37, v106, v107
	v_lshl_add_u64 v[38:39], s[76:77], 0, v[112:113]
	v_pk_mul_f32 v[120:121], v[120:121], v[126:127]
	global_store_dwordx2 v[38:39], v[36:37], off
	v_cvt_pk_bf16_f32 v36, v54, v55
	v_cvt_pk_bf16_f32 v37, v154, v155
	v_lshl_add_u64 v[38:39], s[78:79], 0, v[112:113]
	global_store_dwordx2 v[38:39], v[36:37], off
	v_cvt_pk_bf16_f32 v36, v118, v119
	v_cvt_pk_bf16_f32 v37, v120, v121
	v_lshl_add_u64 v[38:39], s[80:81], 0, v[112:113]
	global_store_dwordx2 v[38:39], v[36:37], off
	v_cvt_pk_bf16_f32 v36, v122, v123
	v_cvt_pk_bf16_f32 v37, v124, v125
	v_lshl_add_u64 v[38:39], s[82:83], 0, v[112:113]
	global_store_dwordx2 v[38:39], v[36:37], off
	v_cvt_pk_bf16_f32 v36, v110, v111
	v_cvt_pk_bf16_f32 v37, v178, v179
	v_lshl_add_u64 v[38:39], s[84:85], 0, v[112:113]
	v_add_u32_e32 v54, s20, v173
	global_store_dwordx2 v[38:39], v[36:37], off
	v_mad_i64_i32 v[36:37], s[10:11], v54, s22, v[60:61]
	v_add_co_u32_e32 v36, vcc, s2, v36
	v_ashrrev_i32_e32 v55, 31, v54
	s_nop 0
	v_addc_co_u32_e32 v37, vcc, 0, v37, vcc
	s_waitcnt vmcnt(6)
	v_mov_b64_e32 v[106:107], v[234:235]
	v_mov_b64_e32 v[110:111], v[236:237]
	v_mov_b64_e32 v[118:119], v[238:239]
	v_mov_b64_e32 v[116:117], v[240:241]
	ds_read2st64_b64 v[36:39], v174 offset0:16 offset1:80
	s_waitcnt lgkmcnt(0)
	v_lshlrev_b32_e32 v58, 16, v38
	v_add_f32_e32 v58, v12, v58
	v_mul_f32_e32 v58, 0xbfb8aa3b, v58
	v_exp_f32_e32 v58, v58
	v_and_b32_e32 v38, 0xffff0000, v38
	v_add_f32_e32 v38, v13, v38
	v_mul_f32_e32 v38, 0xbfb8aa3b, v38
	v_lshlrev_b32_e32 v103, 16, v39
	v_and_b32_e32 v126, 0xffff0000, v39
	v_add_f32_e32 v39, 1.0, v58
	v_exp_f32_e32 v58, v38
	v_lshlrev_b32_e32 v112, 16, v106
	v_add_f32_e32 v58, 1.0, v58
	v_and_b32_e32 v113, 0xffff0000, v106
	v_lshlrev_b32_e32 v120, 16, v107
	v_and_b32_e32 v121, 0xffff0000, v107
	v_rcp_f32_e32 v106, v39
	v_rcp_f32_e32 v107, v58
	v_add_f32_e32 v58, v14, v103
	v_mul_f32_e32 v58, 0xbfb8aa3b, v58
	v_add_f32_e32 v103, v15, v126
	v_lshlrev_b32_e32 v122, 16, v110
	v_and_b32_e32 v123, 0xffff0000, v110
	v_exp_f32_e32 v58, v58
	v_mul_f32_e32 v103, 0xbfb8aa3b, v103
	v_lshlrev_b32_e32 v124, 16, v111
	v_and_b32_e32 v125, 0xffff0000, v111
	v_pk_add_f32 v[38:39], v[108:109], v[112:113] neg_lo:[0,1] neg_hi:[0,1]
	v_pk_add_f32 v[108:109], v[114:115], v[122:123] neg_lo:[0,1] neg_hi:[0,1]
	v_pk_add_f32 v[110:111], v[106:107], -1.0 op_sel_hi:[1,0]
	v_exp_f32_e32 v103, v103
	v_pk_fma_f32 v[108:109], v[20:21], v[108:109], v[122:123]
	v_pk_fma_f32 v[110:111], v[28:29], v[110:111], 1.0 op_sel_hi:[1,1,0]
	v_pk_fma_f32 v[38:39], v[16:17], v[38:39], v[112:113]
	v_pk_mul_f32 v[112:113], v[24:25], v[108:109]
	v_pk_mul_f32 v[108:109], v[108:109], v[110:111]
	v_add_f32_e32 v58, 1.0, v58
	v_pk_mul_f32 v[110:111], v[38:39], v[108:109]
	v_pk_add_f32 v[46:47], v[46:47], v[124:125] neg_lo:[0,1] neg_hi:[0,1]
	v_fma_f32 v127, v32, v110, 0
	v_rcp_f32_e32 v110, v58
	v_add_f32_e32 v58, 1.0, v103
	v_fmac_f32_e32 v127, v33, v111
	v_rcp_f32_e32 v111, v58
	v_pk_fma_f32 v[46:47], v[22:23], v[46:47], v[124:125]
	v_pk_mul_f32 v[122:123], v[112:113], v[112:113]
	v_pk_add_f32 v[44:45], v[44:45], v[120:121] neg_lo:[0,1] neg_hi:[0,1]
	v_pk_mul_f32 v[114:115], v[26:27], v[46:47]
	v_pk_fma_f32 v[44:45], v[18:19], v[44:45], v[120:121]
	v_pk_mul_f32 v[120:121], v[114:115], v[114:115]
	v_add_f32_e32 v58, v122, v123
	v_add_f32_e32 v58, v58, v120
	v_add_f32_e32 v58, v121, v58
	v_pk_add_f32 v[120:121], v[110:111], -1.0 op_sel_hi:[1,0]
	s_nop 0
	v_pk_fma_f32 v[120:121], v[30:31], v[120:121], 1.0 op_sel_hi:[1,1,0]
	v_add_f32_dpp v58, v58, v58 quad_perm:[1,0,3,2] row_mask:0xf bank_mask:0xf bound_ctrl:1
	v_pk_mul_f32 v[46:47], v[46:47], v[120:121]
	s_nop 0
	v_pk_mul_f32 v[120:121], v[44:45], v[46:47]
	v_add_f32_dpp v58, v58, v58 quad_perm:[2,3,0,1] row_mask:0xf bank_mask:0xf bound_ctrl:1
	v_fmac_f32_e32 v127, v34, v120
	v_fmac_f32_e32 v127, v35, v121
	v_add_f32_dpp v58, v58, v58 row_half_mirror row_mask:0xf bank_mask:0xf bound_ctrl:1
	s_nop 0
	v_add_f32_dpp v120, v127, v127 quad_perm:[1,0,3,2] row_mask:0xf bank_mask:0xf bound_ctrl:1
	v_mov_b32_dpp v103, v58 row_mirror row_mask:0xf bank_mask:0xf bound_ctrl:1
	s_nop 0
	v_add_f32_dpp v120, v120, v120 quad_perm:[2,3,0,1] row_mask:0xf bank_mask:0xf bound_ctrl:1
	s_nop 1
	v_add_f32_dpp v120, v120, v120 row_half_mirror row_mask:0xf bank_mask:0xf bound_ctrl:1
	s_nop 1
	v_mov_b32_dpp v121, v120 row_mirror row_mask:0xf bank_mask:0xf bound_ctrl:1
	s_and_saveexec_b64 s[10:11], s[6:7]
	s_cbranch_execz .LBB0_162
	v_lshlrev_b64 v[122:123], 6, v[54:55]
	v_lshl_add_u64 v[122:123], v[98:99], 0, v[122:123]
	v_add_f32_e32 v55, v120, v121
	global_store_dword v[122:123], v55, off
	s_branch .LBB0_162
.LBB0_211:
	s_barrier
	s_and_saveexec_b64 s[4:5], s[0:1]
	s_cbranch_execz .LBB0_217
	s_mov_b64 s[6:7], exec
	buffer_wbl2 sc1
	s_waitcnt vmcnt(0) lgkmcnt(0)
	v_mbcnt_lo_u32_b32 v0, s6, 0
	v_mbcnt_hi_u32_b32 v0, s7, v0
	v_cmp_eq_u32_e32 vcc, 0, v0
	s_and_saveexec_b64 s[8:9], vcc
	s_cbranch_execz .LBB0_214
	s_bcnt1_i32_b64 s2, s[6:7]
	v_mov_b32_e32 v0, 0
	v_mov_b32_e32 v1, s2
	global_atomic_add v0, v1, s[90:91] offset:64
